# x2 + wave reductions: ds_bpermute xor steps replaced by DPP movs / v_permlane16,32_swap in GIN epilogue, conf LayerNorm, fused epilogues (strategy 7)
# speedup vs baseline: 1.0073x; 1.0073x over previous
; __device__ __forceinline__ float dot4(const f32x4& v) { return (v[0] * v[0] + v[1] * v[1]) + (v[2] * v[2] + v[3] * v[3]); }
;     __device__ __forceinline__ void operator()(const f32x4 (&acc)[2][2][4][2], const Unit& u, int wr, int wc, int fr, int fq) const {
;     ...
;                         if (colw >= ZCQ && colw < ZKR) { float sb = dot4(v0) + dot4(v1); sb += __shfl_xor(sb, 16); sb += __shfl_xor(sb, 32);
;                             if (fq == 0) rstat[(size_t)row * 16 + ((colw - ZCQ) >> 5)] = sb; }
.LBB0_389:
	s_andn2_b64 vcc, exec, s[42:43]
	s_cbranch_vccnz .LBB0_393
	v_mul_f32_e32 v147, v127, v127
	v_mul_f32_e32 v150, v129, v129
	v_fmac_f32_e32 v147, v126, v126
	v_fmac_f32_e32 v150, v128, v128
	v_add_f32_e32 v147, v147, v150
	v_mul_f32_e32 v150, v123, v123
	v_mul_f32_e32 v151, v125, v125
	v_fmac_f32_e32 v150, v122, v122
	v_fmac_f32_e32 v151, v124, v124
	v_add_f32_e32 v150, v150, v151
	v_and_b32_e32 v151, 64, v215
	v_add_f32_e32 v147, v150, v147
	v_xor_b32_e32 v150, 16, v215
	v_add_u32_e32 v151, 64, v151
	v_cmp_lt_i32_e32 vcc, v150, v151
	s_nop 1
	v_cndmask_b32_e32 v150, v215, v150, vcc
	v_lshlrev_b32_e32 v150, 2, v150
	v_mov_b32_e32 v150, v147
	s_nop 1
	v_permlane16_swap_b32_e32 v150, v147
	s_waitcnt lgkmcnt(0)
	v_add_f32_e32 v147, v147, v150
	v_xor_b32_e32 v150, 32, v215
	v_cmp_lt_i32_e32 vcc, v150, v151
	s_nop 1
	v_cndmask_b32_e32 v150, v215, v150, vcc
	v_lshlrev_b32_e32 v150, 2, v150
	v_mov_b32_e32 v150, v147
	s_nop 1
	v_permlane32_swap_b32_e32 v150, v147
	s_and_saveexec_b64 s[42:43], s[38:39]
	s_cbranch_execz .LBB0_392
	v_lshl_add_u64 v[152:153], s[50:51], 0, v[148:149]
	s_lshr_b32 s76, s19, 3
	v_lshl_add_u64 v[152:153], v[152:153], 0, s[76:77]
	s_waitcnt lgkmcnt(0)
	v_add_f32_e32 v147, v147, v150
	global_store_dword v[152:153], v147, off

; __device__ __forceinline__ float dot4(const f32x4& v) { return (v[0] * v[0] + v[1] * v[1]) + (v[2] * v[2] + v[3] * v[3]); }
;     __device__ __forceinline__ void operator()(const f32x4 (&acc)[2][2][4][2], const Unit& u, int wr, int wc, int fr, int fq) const {
;     ...
;                         if (colw >= ZCQ && colw < ZKR) { float sb = dot4(v0) + dot4(v1); sb += __shfl_xor(sb, 16); sb += __shfl_xor(sb, 32);
;                             if (fq == 0) rstat[(size_t)row * 16 + ((colw - ZCQ) >> 5)] = sb; }
.LBB0_399:
	s_andn2_b64 vcc, exec, s[66:67]
	s_cbranch_vccnz .LBB0_403
	v_mul_f32_e32 v122, v119, v119
	v_mul_f32_e32 v123, v121, v121
	v_fmac_f32_e32 v122, v118, v118
	v_fmac_f32_e32 v123, v120, v120
	v_add_f32_e32 v122, v122, v123
	v_mul_f32_e32 v123, v115, v115
	v_mul_f32_e32 v124, v117, v117
	v_fmac_f32_e32 v123, v114, v114
	v_fmac_f32_e32 v124, v116, v116
	v_add_f32_e32 v123, v123, v124
	v_and_b32_e32 v124, 64, v215
	v_add_f32_e32 v122, v123, v122
	v_xor_b32_e32 v123, 16, v215
	v_add_u32_e32 v124, 64, v124
	v_cmp_lt_i32_e32 vcc, v123, v124
	s_nop 1
	v_cndmask_b32_e32 v123, v215, v123, vcc
	v_lshlrev_b32_e32 v123, 2, v123
	v_mov_b32_e32 v123, v122
	s_nop 1
	v_permlane16_swap_b32_e32 v123, v122
	s_waitcnt lgkmcnt(0)
	v_add_f32_e32 v122, v122, v123
	v_xor_b32_e32 v123, 32, v215
	v_cmp_lt_i32_e32 vcc, v123, v124
	s_nop 1
	v_cndmask_b32_e32 v123, v215, v123, vcc
	v_lshlrev_b32_e32 v123, 2, v123
	v_mov_b32_e32 v123, v122
	s_nop 1
	v_permlane32_swap_b32_e32 v123, v122
	s_and_saveexec_b64 s[66:67], s[38:39]
	s_cbranch_execz .LBB0_402
	v_lshl_add_u64 v[124:125], s[50:51], 0, v[148:149]
	s_lshr_b32 s76, s19, 3
	v_lshl_add_u64 v[124:125], v[124:125], 0, s[76:77]
	s_waitcnt lgkmcnt(0)
	v_add_f32_e32 v122, v122, v123
	global_store_dword v[124:125], v122, off

; __device__ __forceinline__ float dot4(const f32x4& v) { return (v[0] * v[0] + v[1] * v[1]) + (v[2] * v[2] + v[3] * v[3]); }
;     __device__ __forceinline__ void operator()(const f32x4 (&acc)[2][2][4][2], const Unit& u, int wr, int wc, int fr, int fq) const {
;     ...
;                         if (colw >= ZCQ && colw < ZKR) { float sb = dot4(v0) + dot4(v1); sb += __shfl_xor(sb, 16); sb += __shfl_xor(sb, 32);
;                             if (fq == 0) rstat[(size_t)row * 16 + ((colw - ZCQ) >> 5)] = sb; }
.LBB0_409:
	s_andn2_b64 vcc, exec, s[66:67]
	s_cbranch_vccnz .LBB0_413
	v_mul_f32_e32 v117, v111, v111
	v_mul_f32_e32 v118, v113, v113
	v_fmac_f32_e32 v117, v110, v110
	v_fmac_f32_e32 v118, v112, v112
	v_add_f32_e32 v117, v117, v118
	v_mul_f32_e32 v118, v107, v107
	v_mul_f32_e32 v119, v109, v109
	v_fmac_f32_e32 v118, v106, v106
	v_fmac_f32_e32 v119, v108, v108
	v_add_f32_e32 v118, v118, v119
	v_and_b32_e32 v119, 64, v215
	v_add_f32_e32 v117, v118, v117
	v_xor_b32_e32 v118, 16, v215
	v_add_u32_e32 v119, 64, v119
	v_cmp_lt_i32_e32 vcc, v118, v119
	s_nop 1
	v_cndmask_b32_e32 v118, v215, v118, vcc
	v_lshlrev_b32_e32 v118, 2, v118
	v_mov_b32_e32 v118, v117
	s_nop 1
	v_permlane16_swap_b32_e32 v118, v117
	s_waitcnt lgkmcnt(0)
	v_add_f32_e32 v117, v117, v118
	v_xor_b32_e32 v118, 32, v215
	v_cmp_lt_i32_e32 vcc, v118, v119
	s_nop 1
	v_cndmask_b32_e32 v118, v215, v118, vcc
	v_lshlrev_b32_e32 v118, 2, v118
	v_mov_b32_e32 v118, v117
	s_nop 1
	v_permlane32_swap_b32_e32 v118, v117
	s_and_saveexec_b64 s[66:67], s[38:39]
	s_cbranch_execz .LBB0_412
	v_lshl_add_u64 v[120:121], s[50:51], 0, v[114:115]
	s_lshr_b32 s76, s19, 3
	v_lshl_add_u64 v[120:121], v[120:121], 0, s[76:77]
	s_waitcnt lgkmcnt(0)
	v_add_f32_e32 v117, v117, v118
	global_store_dword v[120:121], v117, off

; __device__ __forceinline__ float dot4(const f32x4& v) { return (v[0] * v[0] + v[1] * v[1]) + (v[2] * v[2] + v[3] * v[3]); }
;     __device__ __forceinline__ void operator()(const f32x4 (&acc)[2][2][4][2], const Unit& u, int wr, int wc, int fr, int fq) const {
;     ...
;                         if (colw >= ZCQ && colw < ZKR) { float sb = dot4(v0) + dot4(v1); sb += __shfl_xor(sb, 16); sb += __shfl_xor(sb, 32);
;                             if (fq == 0) rstat[(size_t)row * 16 + ((colw - ZCQ) >> 5)] = sb; }
.LBB0_419:
	s_andn2_b64 vcc, exec, s[66:67]
	s_cbranch_vccnz .LBB0_423
	v_mul_f32_e32 v106, v103, v103
	v_mul_f32_e32 v107, v105, v105
	v_fmac_f32_e32 v106, v102, v102
	v_fmac_f32_e32 v107, v104, v104
	v_add_f32_e32 v106, v106, v107
	v_mul_f32_e32 v107, v99, v99
	v_mul_f32_e32 v108, v101, v101
	v_fmac_f32_e32 v107, v98, v98
	v_fmac_f32_e32 v108, v100, v100
	v_add_f32_e32 v107, v107, v108
	v_and_b32_e32 v108, 64, v215
	v_add_f32_e32 v106, v107, v106
	v_xor_b32_e32 v107, 16, v215
	v_add_u32_e32 v108, 64, v108
	v_cmp_lt_i32_e32 vcc, v107, v108
	s_nop 1
	v_cndmask_b32_e32 v107, v215, v107, vcc
	v_lshlrev_b32_e32 v107, 2, v107
	v_mov_b32_e32 v107, v106
	s_nop 1
	v_permlane16_swap_b32_e32 v107, v106
	s_waitcnt lgkmcnt(0)
	v_add_f32_e32 v106, v106, v107
	v_xor_b32_e32 v107, 32, v215
	v_cmp_lt_i32_e32 vcc, v107, v108
	s_nop 1
	v_cndmask_b32_e32 v107, v215, v107, vcc
	v_lshlrev_b32_e32 v107, 2, v107
	v_mov_b32_e32 v107, v106
	s_nop 1
	v_permlane32_swap_b32_e32 v107, v106
	s_and_saveexec_b64 s[66:67], s[38:39]
	s_cbranch_execz .LBB0_422
	v_lshl_add_u64 v[108:109], s[50:51], 0, v[114:115]
	s_lshr_b32 s76, s19, 3
	v_lshl_add_u64 v[108:109], v[108:109], 0, s[76:77]
	s_waitcnt lgkmcnt(0)
	v_add_f32_e32 v106, v106, v107
	global_store_dword v[108:109], v106, off

; __device__ __forceinline__ float dot4(const f32x4& v) { return (v[0] * v[0] + v[1] * v[1]) + (v[2] * v[2] + v[3] * v[3]); }
;     __device__ __forceinline__ void operator()(const f32x4 (&acc)[2][2][4][2], const Unit& u, int wr, int wc, int fr, int fq) const {
;     ...
;                         if (colw >= ZCQ && colw < ZKR) { float sb = dot4(v0) + dot4(v1); sb += __shfl_xor(sb, 16); sb += __shfl_xor(sb, 32);
;                             if (fq == 0) rstat[(size_t)row * 16 + ((colw - ZCQ) >> 5)] = sb; }
.LBB0_429:
	s_andn2_b64 vcc, exec, s[66:67]
	s_cbranch_vccnz .LBB0_433
	v_mul_f32_e32 v101, v93, v93
	v_mul_f32_e32 v102, v95, v95
	v_fmac_f32_e32 v101, v92, v92
	v_fmac_f32_e32 v102, v94, v94
	v_add_f32_e32 v101, v101, v102
	v_mul_f32_e32 v102, v89, v89
	v_mul_f32_e32 v103, v91, v91
	v_fmac_f32_e32 v102, v88, v88
	v_fmac_f32_e32 v103, v90, v90
	v_add_f32_e32 v102, v102, v103
	v_and_b32_e32 v103, 64, v215
	v_add_f32_e32 v101, v102, v101
	v_xor_b32_e32 v102, 16, v215
	v_add_u32_e32 v103, 64, v103
	v_cmp_lt_i32_e32 vcc, v102, v103
	s_nop 1
	v_cndmask_b32_e32 v102, v215, v102, vcc
	v_lshlrev_b32_e32 v102, 2, v102
	v_mov_b32_e32 v102, v101
	s_nop 1
	v_permlane16_swap_b32_e32 v102, v101
	s_waitcnt lgkmcnt(0)
	v_add_f32_e32 v101, v101, v102
	v_xor_b32_e32 v102, 32, v215
	v_cmp_lt_i32_e32 vcc, v102, v103
	s_nop 1
	v_cndmask_b32_e32 v102, v215, v102, vcc
	v_lshlrev_b32_e32 v102, 2, v102
	v_mov_b32_e32 v102, v101
	s_nop 1
	v_permlane32_swap_b32_e32 v102, v101
	s_and_saveexec_b64 s[66:67], s[38:39]
	s_cbranch_execz .LBB0_432
	v_lshl_add_u64 v[104:105], s[50:51], 0, v[98:99]
	s_lshr_b32 s76, s19, 3
	v_lshl_add_u64 v[104:105], v[104:105], 0, s[76:77]
	s_waitcnt lgkmcnt(0)
	v_add_f32_e32 v101, v101, v102
	global_store_dword v[104:105], v101, off

; __device__ __forceinline__ float dot4(const f32x4& v) { return (v[0] * v[0] + v[1] * v[1]) + (v[2] * v[2] + v[3] * v[3]); }
;     __device__ __forceinline__ void operator()(const f32x4 (&acc)[2][2][4][2], const Unit& u, int wr, int wc, int fr, int fq) const {
;     ...
;                         if (colw >= ZCQ && colw < ZKR) { float sb = dot4(v0) + dot4(v1); sb += __shfl_xor(sb, 16); sb += __shfl_xor(sb, 32);
;                             if (fq == 0) rstat[(size_t)row * 16 + ((colw - ZCQ) >> 5)] = sb; }
.LBB0_439:
	s_andn2_b64 vcc, exec, s[66:67]
	s_cbranch_vccnz .LBB0_443
	v_mul_f32_e32 v88, v85, v85
	v_mul_f32_e32 v89, v87, v87
	v_fmac_f32_e32 v88, v84, v84
	v_fmac_f32_e32 v89, v86, v86
	v_add_f32_e32 v88, v88, v89
	v_mul_f32_e32 v89, v81, v81
	v_mul_f32_e32 v90, v83, v83
	v_fmac_f32_e32 v89, v80, v80
	v_fmac_f32_e32 v90, v82, v82
	v_add_f32_e32 v89, v89, v90
	v_and_b32_e32 v90, 64, v215
	v_add_f32_e32 v88, v89, v88
	v_xor_b32_e32 v89, 16, v215
	v_add_u32_e32 v90, 64, v90
	v_cmp_lt_i32_e32 vcc, v89, v90
	s_nop 1
	v_cndmask_b32_e32 v89, v215, v89, vcc
	v_lshlrev_b32_e32 v89, 2, v89
	v_mov_b32_e32 v89, v88
	s_nop 1
	v_permlane16_swap_b32_e32 v89, v88
	s_waitcnt lgkmcnt(0)
	v_add_f32_e32 v88, v88, v89
	v_xor_b32_e32 v89, 32, v215
	v_cmp_lt_i32_e32 vcc, v89, v90
	s_nop 1
	v_cndmask_b32_e32 v89, v215, v89, vcc
	v_lshlrev_b32_e32 v89, 2, v89
	v_mov_b32_e32 v89, v88
	s_nop 1
	v_permlane32_swap_b32_e32 v89, v88
	s_and_saveexec_b64 s[66:67], s[38:39]
	s_cbranch_execz .LBB0_442
	v_lshl_add_u64 v[90:91], s[50:51], 0, v[98:99]
	s_lshr_b32 s76, s19, 3
	v_lshl_add_u64 v[90:91], v[90:91], 0, s[76:77]
	s_waitcnt lgkmcnt(0)
	v_add_f32_e32 v88, v88, v89
	global_store_dword v[90:91], v88, off

; __device__ __forceinline__ float dot4(const f32x4& v) { return (v[0] * v[0] + v[1] * v[1]) + (v[2] * v[2] + v[3] * v[3]); }
;     __device__ __forceinline__ void operator()(const f32x4 (&acc)[2][2][4][2], const Unit& u, int wr, int wc, int fr, int fq) const {
;     ...
;                         if (colw >= ZCQ && colw < ZKR) { float sb = dot4(v0) + dot4(v1); sb += __shfl_xor(sb, 16); sb += __shfl_xor(sb, 32);
;                             if (fq == 0) rstat[(size_t)row * 16 + ((colw - ZCQ) >> 5)] = sb; }
.LBB0_449:
	s_andn2_b64 vcc, exec, s[66:67]
	s_cbranch_vccnz .LBB0_453
	v_mul_f32_e32 v83, v77, v77
	v_mul_f32_e32 v84, v79, v79
	v_fmac_f32_e32 v83, v76, v76
	v_fmac_f32_e32 v84, v78, v78
	v_add_f32_e32 v83, v83, v84
	v_mul_f32_e32 v84, v73, v73
	v_mul_f32_e32 v85, v75, v75
	v_fmac_f32_e32 v84, v72, v72
	v_fmac_f32_e32 v85, v74, v74
	v_add_f32_e32 v84, v84, v85
	v_and_b32_e32 v85, 64, v215
	v_add_f32_e32 v83, v84, v83
	v_xor_b32_e32 v84, 16, v215
	v_add_u32_e32 v85, 64, v85
	v_cmp_lt_i32_e32 vcc, v84, v85
	s_nop 1
	v_cndmask_b32_e32 v84, v215, v84, vcc
	v_lshlrev_b32_e32 v84, 2, v84
	v_mov_b32_e32 v84, v83
	s_nop 1
	v_permlane16_swap_b32_e32 v84, v83
	s_waitcnt lgkmcnt(0)
	v_add_f32_e32 v83, v83, v84
	v_xor_b32_e32 v84, 32, v215
	v_cmp_lt_i32_e32 vcc, v84, v85
	s_nop 1
	v_cndmask_b32_e32 v84, v215, v84, vcc
	v_lshlrev_b32_e32 v84, 2, v84
	v_mov_b32_e32 v84, v83
	s_nop 1
	v_permlane32_swap_b32_e32 v84, v83
	s_and_saveexec_b64 s[66:67], s[38:39]
	s_cbranch_execz .LBB0_452
	v_lshl_add_u64 v[86:87], s[50:51], 0, v[80:81]
	s_lshr_b32 s76, s19, 3
	v_lshl_add_u64 v[86:87], v[86:87], 0, s[76:77]
	s_waitcnt lgkmcnt(0)
	v_add_f32_e32 v83, v83, v84
	global_store_dword v[86:87], v83, off

; __device__ __forceinline__ float dot4(const f32x4& v) { return (v[0] * v[0] + v[1] * v[1]) + (v[2] * v[2] + v[3] * v[3]); }
;     __device__ __forceinline__ void operator()(const f32x4 (&acc)[2][2][4][2], const Unit& u, int wr, int wc, int fr, int fq) const {
;     ...
;                         if (colw >= ZCQ && colw < ZKR) { float sb = dot4(v0) + dot4(v1); sb += __shfl_xor(sb, 16); sb += __shfl_xor(sb, 32);
;                             if (fq == 0) rstat[(size_t)row * 16 + ((colw - ZCQ) >> 5)] = sb; }
.LBB0_459:
	s_andn2_b64 vcc, exec, s[66:67]
	s_cbranch_vccnz .LBB0_463
	v_mul_f32_e32 v72, v69, v69
	v_mul_f32_e32 v73, v71, v71
	v_fmac_f32_e32 v72, v68, v68
	v_fmac_f32_e32 v73, v70, v70
	v_add_f32_e32 v72, v72, v73
	v_mul_f32_e32 v73, v65, v65
	v_mul_f32_e32 v74, v67, v67
	v_fmac_f32_e32 v73, v64, v64
	v_fmac_f32_e32 v74, v66, v66
	v_add_f32_e32 v73, v73, v74
	v_and_b32_e32 v74, 64, v215
	v_add_f32_e32 v72, v73, v72
	v_xor_b32_e32 v73, 16, v215
	v_add_u32_e32 v74, 64, v74
	v_cmp_lt_i32_e32 vcc, v73, v74
	s_nop 1
	v_cndmask_b32_e32 v73, v215, v73, vcc
	v_lshlrev_b32_e32 v73, 2, v73
	v_mov_b32_e32 v73, v72
	s_nop 1
	v_permlane16_swap_b32_e32 v73, v72
	s_waitcnt lgkmcnt(0)
	v_add_f32_e32 v72, v72, v73
	v_xor_b32_e32 v73, 32, v215
	v_cmp_lt_i32_e32 vcc, v73, v74
	s_nop 1
	v_cndmask_b32_e32 v73, v215, v73, vcc
	v_lshlrev_b32_e32 v73, 2, v73
	v_mov_b32_e32 v73, v72
	s_nop 1
	v_permlane32_swap_b32_e32 v73, v72
	s_and_saveexec_b64 s[66:67], s[38:39]
	s_cbranch_execz .LBB0_462
	v_lshl_add_u64 v[74:75], s[50:51], 0, v[80:81]
	s_lshr_b32 s76, s18, 3
	v_lshl_add_u64 v[74:75], v[74:75], 0, s[76:77]
	s_waitcnt lgkmcnt(0)
	v_add_f32_e32 v72, v72, v73
	global_store_dword v[74:75], v72, off

; __device__ __forceinline__ float dot4(const f32x4& v) { return (v[0] * v[0] + v[1] * v[1]) + (v[2] * v[2] + v[3] * v[3]); }
;     __device__ __forceinline__ void operator()(const f32x4 (&acc)[2][2][4][2], const Unit& u, int wr, int wc, int fr, int fq) const {
;     ...
;                         if (colw >= ZCQ && colw < ZKR) { float sb = dot4(v0) + dot4(v1); sb += __shfl_xor(sb, 16); sb += __shfl_xor(sb, 32);
;                             if (fq == 0) rstat[(size_t)row * 16 + ((colw - ZCQ) >> 5)] = sb; }
.LBB0_469:
	s_andn2_b64 vcc, exec, s[66:67]
	s_cbranch_vccnz .LBB0_473
	v_mul_f32_e32 v67, v61, v61
	v_mul_f32_e32 v68, v63, v63
	v_fmac_f32_e32 v67, v60, v60
	v_fmac_f32_e32 v68, v62, v62
	v_add_f32_e32 v67, v67, v68
	v_mul_f32_e32 v68, v57, v57
	v_mul_f32_e32 v69, v59, v59
	v_fmac_f32_e32 v68, v56, v56
	v_fmac_f32_e32 v69, v58, v58
	v_add_f32_e32 v68, v68, v69
	v_and_b32_e32 v69, 64, v215
	v_add_f32_e32 v67, v68, v67
	v_xor_b32_e32 v68, 16, v215
	v_add_u32_e32 v69, 64, v69
	v_cmp_lt_i32_e32 vcc, v68, v69
	s_nop 1
	v_cndmask_b32_e32 v68, v215, v68, vcc
	v_lshlrev_b32_e32 v68, 2, v68
	v_mov_b32_e32 v68, v67
	s_nop 1
	v_permlane16_swap_b32_e32 v68, v67
	s_waitcnt lgkmcnt(0)
	v_add_f32_e32 v67, v67, v68
	v_xor_b32_e32 v68, 32, v215
	v_cmp_lt_i32_e32 vcc, v68, v69
	s_nop 1
	v_cndmask_b32_e32 v68, v215, v68, vcc
	v_lshlrev_b32_e32 v68, 2, v68
	v_mov_b32_e32 v68, v67
	s_nop 1
	v_permlane32_swap_b32_e32 v68, v67
	s_and_saveexec_b64 s[66:67], s[38:39]
	s_cbranch_execz .LBB0_472
	v_lshl_add_u64 v[70:71], s[50:51], 0, v[64:65]
	s_lshr_b32 s76, s18, 3
	v_lshl_add_u64 v[70:71], v[70:71], 0, s[76:77]
	s_waitcnt lgkmcnt(0)
	v_add_f32_e32 v67, v67, v68
	global_store_dword v[70:71], v67, off

; __device__ __forceinline__ float dot4(const f32x4& v) { return (v[0] * v[0] + v[1] * v[1]) + (v[2] * v[2] + v[3] * v[3]); }
;     __device__ __forceinline__ void operator()(const f32x4 (&acc)[2][2][4][2], const Unit& u, int wr, int wc, int fr, int fq) const {
;     ...
;                         if (colw >= ZCQ && colw < ZKR) { float sb = dot4(v0) + dot4(v1); sb += __shfl_xor(sb, 16); sb += __shfl_xor(sb, 32);
;                             if (fq == 0) rstat[(size_t)row * 16 + ((colw - ZCQ) >> 5)] = sb; }
.LBB0_479:
	s_andn2_b64 vcc, exec, s[66:67]
	s_cbranch_vccnz .LBB0_483
	v_mul_f32_e32 v56, v53, v53
	v_mul_f32_e32 v57, v55, v55
	v_fmac_f32_e32 v56, v52, v52
	v_fmac_f32_e32 v57, v54, v54
	v_add_f32_e32 v56, v56, v57
	v_mul_f32_e32 v57, v49, v49
	v_mul_f32_e32 v58, v51, v51
	v_fmac_f32_e32 v57, v48, v48
	v_fmac_f32_e32 v58, v50, v50
	v_add_f32_e32 v57, v57, v58
	v_and_b32_e32 v58, 64, v215
	v_add_f32_e32 v56, v57, v56
	v_xor_b32_e32 v57, 16, v215
	v_add_u32_e32 v58, 64, v58
	v_cmp_lt_i32_e32 vcc, v57, v58
	s_nop 1
	v_cndmask_b32_e32 v57, v215, v57, vcc
	v_lshlrev_b32_e32 v57, 2, v57
	v_mov_b32_e32 v57, v56
	s_nop 1
	v_permlane16_swap_b32_e32 v57, v56
	s_waitcnt lgkmcnt(0)
	v_add_f32_e32 v56, v56, v57
	v_xor_b32_e32 v57, 32, v215
	v_cmp_lt_i32_e32 vcc, v57, v58
	s_nop 1
	v_cndmask_b32_e32 v57, v215, v57, vcc
	v_lshlrev_b32_e32 v57, 2, v57
	v_mov_b32_e32 v57, v56
	s_nop 1
	v_permlane32_swap_b32_e32 v57, v56
	s_and_saveexec_b64 s[66:67], s[38:39]
	s_cbranch_execz .LBB0_482
	v_lshl_add_u64 v[58:59], s[50:51], 0, v[64:65]
	s_lshr_b32 s76, s18, 3
	v_lshl_add_u64 v[58:59], v[58:59], 0, s[76:77]
	s_waitcnt lgkmcnt(0)
	v_add_f32_e32 v56, v56, v57
	global_store_dword v[58:59], v56, off

; __device__ __forceinline__ float dot4(const f32x4& v) { return (v[0] * v[0] + v[1] * v[1]) + (v[2] * v[2] + v[3] * v[3]); }
;     __device__ __forceinline__ void operator()(const f32x4 (&acc)[2][2][4][2], const Unit& u, int wr, int wc, int fr, int fq) const {
;     ...
;                         if (colw >= ZCQ && colw < ZKR) { float sb = dot4(v0) + dot4(v1); sb += __shfl_xor(sb, 16); sb += __shfl_xor(sb, 32);
;                             if (fq == 0) rstat[(size_t)row * 16 + ((colw - ZCQ) >> 5)] = sb; }
.LBB0_489:
	s_andn2_b64 vcc, exec, s[66:67]
	s_cbranch_vccnz .LBB0_493
	v_mul_f32_e32 v51, v45, v45
	v_mul_f32_e32 v52, v47, v47
	v_fmac_f32_e32 v51, v44, v44
	v_fmac_f32_e32 v52, v46, v46
	v_add_f32_e32 v51, v51, v52
	v_mul_f32_e32 v52, v41, v41
	v_mul_f32_e32 v53, v43, v43
	v_fmac_f32_e32 v52, v40, v40
	v_fmac_f32_e32 v53, v42, v42
	v_add_f32_e32 v52, v52, v53
	v_and_b32_e32 v53, 64, v215
	v_add_f32_e32 v51, v52, v51
	v_xor_b32_e32 v52, 16, v215
	v_add_u32_e32 v53, 64, v53
	v_cmp_lt_i32_e32 vcc, v52, v53
	s_nop 1
	v_cndmask_b32_e32 v52, v215, v52, vcc
	v_lshlrev_b32_e32 v52, 2, v52
	v_mov_b32_e32 v52, v51
	s_nop 1
	v_permlane16_swap_b32_e32 v52, v51
	s_waitcnt lgkmcnt(0)
	v_add_f32_e32 v51, v51, v52
	v_xor_b32_e32 v52, 32, v215
	v_cmp_lt_i32_e32 vcc, v52, v53
	s_nop 1
	v_cndmask_b32_e32 v52, v215, v52, vcc
	v_lshlrev_b32_e32 v52, 2, v52
	v_mov_b32_e32 v52, v51
	s_nop 1
	v_permlane32_swap_b32_e32 v52, v51
	s_and_saveexec_b64 s[66:67], s[38:39]
	s_cbranch_execz .LBB0_492
	v_lshl_add_u64 v[54:55], s[50:51], 0, v[48:49]
	s_lshr_b32 s76, s18, 3
	v_lshl_add_u64 v[54:55], v[54:55], 0, s[76:77]
	s_waitcnt lgkmcnt(0)
	v_add_f32_e32 v51, v51, v52
	global_store_dword v[54:55], v51, off

; __device__ __forceinline__ float dot4(const f32x4& v) { return (v[0] * v[0] + v[1] * v[1]) + (v[2] * v[2] + v[3] * v[3]); }
;     __device__ __forceinline__ void operator()(const f32x4 (&acc)[2][2][4][2], const Unit& u, int wr, int wc, int fr, int fq) const {
;     ...
;                         if (colw >= ZCQ && colw < ZKR) { float sb = dot4(v0) + dot4(v1); sb += __shfl_xor(sb, 16); sb += __shfl_xor(sb, 32);
;                             if (fq == 0) rstat[(size_t)row * 16 + ((colw - ZCQ) >> 5)] = sb; }
.LBB0_499:
	s_andn2_b64 vcc, exec, s[66:67]
	s_cbranch_vccnz .LBB0_503
	v_mul_f32_e32 v40, v37, v37
	v_mul_f32_e32 v41, v39, v39
	v_fmac_f32_e32 v40, v36, v36
	v_fmac_f32_e32 v41, v38, v38
	v_add_f32_e32 v40, v40, v41
	v_mul_f32_e32 v41, v33, v33
	v_mul_f32_e32 v42, v35, v35
	v_fmac_f32_e32 v41, v32, v32
	v_fmac_f32_e32 v42, v34, v34
	v_add_f32_e32 v41, v41, v42
	v_and_b32_e32 v42, 64, v215
	v_add_f32_e32 v40, v41, v40
	v_xor_b32_e32 v41, 16, v215
	v_add_u32_e32 v42, 64, v42
	v_cmp_lt_i32_e32 vcc, v41, v42
	s_nop 1
	v_cndmask_b32_e32 v41, v215, v41, vcc
	v_lshlrev_b32_e32 v41, 2, v41
	v_mov_b32_e32 v41, v40
	s_nop 1
	v_permlane16_swap_b32_e32 v41, v40
	s_waitcnt lgkmcnt(0)
	v_add_f32_e32 v40, v40, v41
	v_xor_b32_e32 v41, 32, v215
	v_cmp_lt_i32_e32 vcc, v41, v42
	s_nop 1
	v_cndmask_b32_e32 v41, v215, v41, vcc
	v_lshlrev_b32_e32 v41, 2, v41
	v_mov_b32_e32 v41, v40
	s_nop 1
	v_permlane32_swap_b32_e32 v41, v40
	s_and_saveexec_b64 s[66:67], s[38:39]
	s_cbranch_execz .LBB0_502
	v_lshl_add_u64 v[42:43], s[50:51], 0, v[48:49]
	s_lshr_b32 s76, s18, 3
	v_lshl_add_u64 v[42:43], v[42:43], 0, s[76:77]
	s_waitcnt lgkmcnt(0)
	v_add_f32_e32 v40, v40, v41
	global_store_dword v[42:43], v40, off

; __device__ __forceinline__ float dot4(const f32x4& v) { return (v[0] * v[0] + v[1] * v[1]) + (v[2] * v[2] + v[3] * v[3]); }
;     __device__ __forceinline__ void operator()(const f32x4 (&acc)[2][2][4][2], const Unit& u, int wr, int wc, int fr, int fq) const {
;     ...
;                         if (colw >= ZCQ && colw < ZKR) { float sb = dot4(v0) + dot4(v1); sb += __shfl_xor(sb, 16); sb += __shfl_xor(sb, 32);
;                             if (fq == 0) rstat[(size_t)row * 16 + ((colw - ZCQ) >> 5)] = sb; }
.LBB0_509:
	s_andn2_b64 vcc, exec, s[66:67]
	s_cbranch_vccnz .LBB0_513
	v_mul_f32_e32 v35, v29, v29
	v_mul_f32_e32 v36, v31, v31
	v_fmac_f32_e32 v35, v28, v28
	v_fmac_f32_e32 v36, v30, v30
	v_add_f32_e32 v35, v35, v36
	v_mul_f32_e32 v36, v25, v25
	v_mul_f32_e32 v37, v27, v27
	v_fmac_f32_e32 v36, v24, v24
	v_fmac_f32_e32 v37, v26, v26
	v_add_f32_e32 v36, v36, v37
	v_and_b32_e32 v37, 64, v215
	v_add_f32_e32 v35, v36, v35
	v_xor_b32_e32 v36, 16, v215
	v_add_u32_e32 v37, 64, v37
	v_cmp_lt_i32_e32 vcc, v36, v37
	s_nop 1
	v_cndmask_b32_e32 v36, v215, v36, vcc
	v_lshlrev_b32_e32 v36, 2, v36
	v_mov_b32_e32 v36, v35
	s_nop 1
	v_permlane16_swap_b32_e32 v36, v35
	s_waitcnt lgkmcnt(0)
	v_add_f32_e32 v35, v35, v36
	v_xor_b32_e32 v36, 32, v215
	v_cmp_lt_i32_e32 vcc, v36, v37
	s_nop 1
	v_cndmask_b32_e32 v36, v215, v36, vcc
	v_lshlrev_b32_e32 v36, 2, v36
	v_mov_b32_e32 v36, v35
	s_nop 1
	v_permlane32_swap_b32_e32 v36, v35
	s_and_saveexec_b64 s[66:67], s[38:39]
	s_cbranch_execz .LBB0_512
	v_lshl_add_u64 v[38:39], s[50:51], 0, v[32:33]
	s_lshr_b32 s76, s18, 3
	v_lshl_add_u64 v[38:39], v[38:39], 0, s[76:77]
	s_waitcnt lgkmcnt(0)
	v_add_f32_e32 v35, v35, v36
	global_store_dword v[38:39], v35, off

; __device__ __forceinline__ float dot4(const f32x4& v) { return (v[0] * v[0] + v[1] * v[1]) + (v[2] * v[2] + v[3] * v[3]); }
;     __device__ __forceinline__ void operator()(const f32x4 (&acc)[2][2][4][2], const Unit& u, int wr, int wc, int fr, int fq) const {
;     ...
;                         if (colw >= ZCQ && colw < ZKR) { float sb = dot4(v0) + dot4(v1); sb += __shfl_xor(sb, 16); sb += __shfl_xor(sb, 32);
;                             if (fq == 0) rstat[(size_t)row * 16 + ((colw - ZCQ) >> 5)] = sb; }
.LBB0_519:
	s_andn2_b64 vcc, exec, s[66:67]
	s_cbranch_vccnz .LBB0_523
	v_mul_f32_e32 v24, v21, v21
	v_mul_f32_e32 v25, v23, v23
	v_fmac_f32_e32 v24, v20, v20
	v_fmac_f32_e32 v25, v22, v22
	v_add_f32_e32 v24, v24, v25
	v_mul_f32_e32 v25, v17, v17
	v_mul_f32_e32 v26, v19, v19
	v_fmac_f32_e32 v25, v16, v16
	v_fmac_f32_e32 v26, v18, v18
	v_add_f32_e32 v25, v25, v26
	v_and_b32_e32 v26, 64, v215
	v_add_f32_e32 v24, v25, v24
	v_xor_b32_e32 v25, 16, v215
	v_add_u32_e32 v26, 64, v26
	v_cmp_lt_i32_e32 vcc, v25, v26
	s_nop 1
	v_cndmask_b32_e32 v25, v215, v25, vcc
	v_lshlrev_b32_e32 v25, 2, v25
	v_mov_b32_e32 v25, v24
	s_nop 1
	v_permlane16_swap_b32_e32 v25, v24
	s_waitcnt lgkmcnt(0)
	v_add_f32_e32 v24, v24, v25
	v_xor_b32_e32 v25, 32, v215
	v_cmp_lt_i32_e32 vcc, v25, v26
	s_nop 1
	v_cndmask_b32_e32 v25, v215, v25, vcc
	v_lshlrev_b32_e32 v25, 2, v25
	v_mov_b32_e32 v25, v24
	s_nop 1
	v_permlane32_swap_b32_e32 v25, v24
	s_and_saveexec_b64 s[66:67], s[38:39]
	s_cbranch_execz .LBB0_522
	v_lshl_add_u64 v[26:27], s[50:51], 0, v[32:33]
	s_lshr_b32 s76, s18, 3
	v_lshl_add_u64 v[26:27], v[26:27], 0, s[76:77]
	s_waitcnt lgkmcnt(0)
	v_add_f32_e32 v24, v24, v25
	global_store_dword v[26:27], v24, off

; __device__ __forceinline__ float dot4(const f32x4& v) { return (v[0] * v[0] + v[1] * v[1]) + (v[2] * v[2] + v[3] * v[3]); }
;     __device__ __forceinline__ void operator()(const f32x4 (&acc)[2][2][4][2], const Unit& u, int wr, int wc, int fr, int fq) const {
;     ...
;                         if (colw >= ZCQ && colw < ZKR) { float sb = dot4(v0) + dot4(v1); sb += __shfl_xor(sb, 16); sb += __shfl_xor(sb, 32);
;                             if (fq == 0) rstat[(size_t)row * 16 + ((colw - ZCQ) >> 5)] = sb; }
.LBB0_529:
	s_andn2_b64 vcc, exec, s[66:67]
	s_cbranch_vccnz .LBB0_533
	v_mul_f32_e32 v19, v13, v13
	v_mul_f32_e32 v20, v15, v15
	v_fmac_f32_e32 v19, v12, v12
	v_fmac_f32_e32 v20, v14, v14
	v_add_f32_e32 v19, v19, v20
	v_mul_f32_e32 v20, v9, v9
	v_mul_f32_e32 v21, v11, v11
	v_fmac_f32_e32 v20, v8, v8
	v_fmac_f32_e32 v21, v10, v10
	v_add_f32_e32 v20, v20, v21
	v_and_b32_e32 v21, 64, v215
	v_add_f32_e32 v19, v20, v19
	v_xor_b32_e32 v20, 16, v215
	v_add_u32_e32 v21, 64, v21
	v_cmp_lt_i32_e32 vcc, v20, v21
	s_nop 1
	v_cndmask_b32_e32 v20, v215, v20, vcc
	v_lshlrev_b32_e32 v20, 2, v20
	v_mov_b32_e32 v20, v19
	s_nop 1
	v_permlane16_swap_b32_e32 v20, v19
	s_waitcnt lgkmcnt(0)
	v_add_f32_e32 v19, v19, v20
	v_xor_b32_e32 v20, 32, v215
	v_cmp_lt_i32_e32 vcc, v20, v21
	s_nop 1
	v_cndmask_b32_e32 v20, v215, v20, vcc
	v_lshlrev_b32_e32 v20, 2, v20
	v_mov_b32_e32 v20, v19
	s_nop 1
	v_permlane32_swap_b32_e32 v20, v19
	s_and_saveexec_b64 s[66:67], s[38:39]
	s_cbranch_execz .LBB0_532
	v_lshl_add_u64 v[22:23], s[50:51], 0, v[16:17]
	s_lshr_b32 s76, s18, 3
	v_lshl_add_u64 v[22:23], v[22:23], 0, s[76:77]
	s_waitcnt lgkmcnt(0)
	v_add_f32_e32 v19, v19, v20
	global_store_dword v[22:23], v19, off

; __device__ __forceinline__ float dot4(const f32x4& v) { return (v[0] * v[0] + v[1] * v[1]) + (v[2] * v[2] + v[3] * v[3]); }
;     __device__ __forceinline__ void operator()(const f32x4 (&acc)[2][2][4][2], const Unit& u, int wr, int wc, int fr, int fq) const {
;     ...
;                         if (colw >= ZCQ && colw < ZKR) { float sb = dot4(v0) + dot4(v1); sb += __shfl_xor(sb, 16); sb += __shfl_xor(sb, 32);
;                             if (fq == 0) rstat[(size_t)row * 16 + ((colw - ZCQ) >> 5)] = sb; }
.LBB0_539:
	s_andn2_b64 vcc, exec, s[42:43]
	s_cbranch_vccnz .LBB0_543
	v_mul_f32_e32 v8, v5, v5
	v_mul_f32_e32 v9, v7, v7
	v_fmac_f32_e32 v8, v4, v4
	v_fmac_f32_e32 v9, v6, v6
	v_add_f32_e32 v8, v8, v9
	v_mul_f32_e32 v9, v1, v1
	v_mul_f32_e32 v10, v3, v3
	v_fmac_f32_e32 v9, v0, v0
	v_fmac_f32_e32 v10, v2, v2
	v_add_f32_e32 v9, v9, v10
	v_and_b32_e32 v10, 64, v215
	v_add_f32_e32 v8, v9, v8
	v_xor_b32_e32 v9, 16, v215
	v_add_u32_e32 v10, 64, v10
	v_cmp_lt_i32_e32 vcc, v9, v10
	s_nop 1
	v_cndmask_b32_e32 v9, v215, v9, vcc
	v_lshlrev_b32_e32 v9, 2, v9
	v_mov_b32_e32 v9, v8
	s_nop 1
	v_permlane16_swap_b32_e32 v9, v8
	s_waitcnt lgkmcnt(0)
	v_add_f32_e32 v8, v8, v9
	v_xor_b32_e32 v9, 32, v215
	v_cmp_lt_i32_e32 vcc, v9, v10
	s_nop 1
	v_cndmask_b32_e32 v9, v215, v9, vcc
	v_lshlrev_b32_e32 v9, 2, v9
	v_mov_b32_e32 v9, v8
	s_nop 1
	v_permlane32_swap_b32_e32 v9, v8
	s_and_saveexec_b64 s[42:43], s[38:39]
	s_cbranch_execz .LBB0_542
	v_lshl_add_u64 v[10:11], s[50:51], 0, v[16:17]
	s_lshr_b32 s76, s18, 3
	v_lshl_add_u64 v[10:11], v[10:11], 0, s[76:77]
	s_waitcnt lgkmcnt(0)
	v_add_f32_e32 v8, v8, v9
	global_store_dword v[10:11], v8, off

; __device__ __forceinline__ void sconv_load(SconvRaw& R, const bf16_t* Z, int r0, int q, int tid) {
;     const int row = r0 + (tid >> 5), c0 = ((tid & 31) + 32 * q) * 8;
;     const int s0 = row < ML ? (row & ~(SEQ - 1)) : ML + ((row - ML) & ~(CTX - 1)), s1 = s0 + (row < ML ? SEQ : CTX);
; #pragma unroll
;     for (int j = 0; j < 3; ++j) { int rr = row + j - 1; rr = rr < s0 ? s0 : (rr >= s1 ? s1 - 1 : rr);
;     ...
;     R.bg = *(const u32x4*)(Z + (size_t)row * INWP + ZSB + c0);
; __device__ __forceinline__ void conf_loop(LAS unsigned char* lds, const Params& P, int layer, int first, int nitems, int G, int tid, int lane, int wave) {
;     ...
;             SconvRaw SR; sconv_load(SR, Z, r0, g8, tid);
;             float win[38];
; #pragma unroll
;             for (int i = 0; i < 38; ++i) win[i] = UB[(g8 * 8 + i) * 512 + c];
; #pragma unroll
;             for (int r = 0; r < 8; ++r) { float y = bias;
; #pragma unroll
;                 for (int j = 0; j < 31; ++j) y += w[j] * win[r + j];
;                 YB[(g8 * 8 + r) * 512 + c] = y; }
.LBB0_929:
	v_add_u32_e32 v64, s66, v229
	v_cmp_gt_i32_e32 vcc, s90, v64
	v_mov_b32_e32 v65, 0x100
	v_mov_b32_e32 v66, 0x1000
	v_cndmask_b32_e32 v65, v65, v66, vcc
	v_mov_b32_e32 v66, 0x7fffff00
	v_mov_b32_e32 v67, 0xfffff000
	v_cndmask_b32_e32 v66, v66, v67, vcc
	v_and_b32_e32 v70, v66, v64
	v_add_u32_e32 v71, v70, v65
	v_min_i32_e32 v65, v64, v71
	v_cmp_gt_i32_e32 vcc, v64, v70
	v_add_u32_e32 v65, -1, v65
	v_mov_b64_e32 v[66:67], s[62:63]
	v_cndmask_b32_e32 v65, v70, v65, vcc
	v_mad_i64_i32 v[68:69], s[18:19], v65, s12, v[66:67]
	v_add_u32_e32 v65, 1, v64
	v_min_i32_e32 v65, v65, v71
	v_cmp_lt_i32_e64 s[50:51], v64, v70
	v_add_u32_e32 v65, -1, v65
	s_mov_b64 s[20:21], 0x1c40
	s_mov_b64 s[24:25], 0x2040
	v_cndmask_b32_e64 v65, v65, v70, s[50:51]
	v_add_u32_e32 v72, 2, v64
	v_lshl_add_u64 v[138:139], v[68:69], 0, s[20:21]
	v_lshl_add_u64 v[136:137], v[68:69], 0, s[24:25]
	v_mad_i64_i32 v[68:69], s[18:19], v65, s12, v[66:67]
	v_min_i32_e32 v65, v72, v71
	v_cmp_gt_i32_e64 s[50:51], v72, v70
	v_add_u32_e32 v65, -1, v65
	v_lshl_add_u64 v[142:143], v[68:69], 0, s[20:21]
	v_cndmask_b32_e64 v65, v70, v65, s[50:51]
	v_lshl_add_u64 v[140:141], v[68:69], 0, s[24:25]
	v_mad_i64_i32 v[68:69], s[18:19], v65, s12, v[66:67]
	v_mad_i64_i32 v[66:67], s[18:19], v64, s12, v[66:67]
	s_mov_b64 s[18:19], 0x1840
	v_cmp_le_i32_e64 s[52:53], v72, v71
	v_ashrrev_i32_e32 v65, 31, v64
	v_lshl_add_u64 v[146:147], v[66:67], 0, s[18:19]
	s_and_b64 s[18:19], s[50:51], s[52:53]
	v_cmp_le_i32_e64 s[50:51], v64, v71
	v_cndmask_b32_e64 v130, 0, 1.0, s[18:19]
	s_and_b64 s[18:19], vcc, s[50:51]
	v_cmp_ge_i32_e32 vcc, v64, v70
	v_cmp_lt_i32_e64 s[50:51], v64, v71
	v_lshlrev_b64 v[150:151], 12, v[64:65]
	v_lshl_add_u64 v[64:65], v[138:139], 0, v[96:97]
	global_load_dwordx4 v[76:79], v[64:65], off
	v_lshl_add_u64 v[64:65], v[136:137], 0, v[96:97]
	global_load_dwordx4 v[88:91], v[64:65], off
	v_lshl_add_u64 v[64:65], v[142:143], 0, v[96:97]
	v_lshl_add_u64 v[148:149], v[68:69], 0, s[20:21]
	v_lshl_add_u64 v[144:145], v[68:69], 0, s[24:25]
	global_load_dwordx4 v[68:71], v[64:65], off
	v_lshl_add_u64 v[64:65], v[140:141], 0, v[96:97]
	global_load_dwordx4 v[72:75], v[64:65], off
	v_lshl_add_u64 v[64:65], v[148:149], 0, v[96:97]
	global_load_dwordx4 v[80:83], v[64:65], off
	v_lshl_add_u64 v[64:65], v[144:145], 0, v[96:97]
	global_load_dwordx4 v[84:87], v[64:65], off
	v_lshl_add_u64 v[64:65], v[146:147], 0, v[96:97]
	global_load_dwordx4 v[64:67], v[64:65], off
	ds_read2st64_b32 v[200:201], v131 offset1:8
	ds_read2st64_b32 v[202:203], v131 offset0:16 offset1:24
	ds_read2st64_b32 v[154:155], v131 offset0:32 offset1:40
	ds_read2st64_b32 v[152:153], v131 offset0:48 offset1:56
	ds_read2st64_b32 v[116:117], v131 offset0:64 offset1:72
	ds_read2st64_b32 v[114:115], v131 offset0:80 offset1:88
	ds_read2st64_b32 v[112:113], v131 offset0:96 offset1:104
	ds_read2st64_b32 v[110:111], v131 offset0:112 offset1:120
	ds_read2st64_b32 v[108:109], v131 offset0:128 offset1:136
	ds_read2st64_b32 v[106:107], v131 offset0:144 offset1:152
	ds_read2st64_b32 v[104:105], v131 offset0:160 offset1:168
	ds_read2st64_b32 v[102:103], v131 offset0:176 offset1:184
	ds_read2st64_b32 v[100:101], v131 offset0:192 offset1:200
	ds_read2st64_b32 v[98:99], v131 offset0:208 offset1:216
	ds_read2st64_b32 v[94:95], v131 offset0:224 offset1:232
	ds_read2st64_b32 v[92:93], v131 offset0:240 offset1:248
	ds_read_b32 v127, v194
	ds_read_b32 v129, v195
	ds_read_b32 v230, v196
	ds_read_b32 v231, v197
	ds_read_b32 v232, v206
	ds_read_b32 v233, v207
	s_waitcnt lgkmcnt(14)
	v_fma_f32 v200, v172, v200, v187
	v_fmac_f32_e32 v200, v173, v201
	v_fma_f32 v201, v172, v201, v187
	v_fmac_f32_e32 v201, v173, v202
	v_fmac_f32_e32 v200, v156, v202
	v_fmac_f32_e32 v201, v156, v203
	v_fmac_f32_e32 v200, v174, v203
	v_fmac_f32_e32 v201, v174, v154
	v_fmac_f32_e32 v200, v157, v154
	v_fmac_f32_e32 v201, v157, v155
	v_fmac_f32_e32 v200, v158, v155
	v_fmac_f32_e32 v201, v158, v152
	v_fmac_f32_e32 v200, v159, v152
	v_fmac_f32_e32 v201, v159, v153
	v_fmac_f32_e32 v200, v175, v153
	v_fmac_f32_e32 v201, v175, v116
	v_fmac_f32_e32 v200, v160, v116
	v_fmac_f32_e32 v201, v160, v117
	v_fmac_f32_e32 v200, v161, v117
	v_fmac_f32_e32 v201, v161, v114
	v_fmac_f32_e32 v200, v162, v114
	v_fmac_f32_e32 v201, v162, v115
	v_fmac_f32_e32 v200, v176, v115
	v_fmac_f32_e32 v201, v176, v112
	v_fmac_f32_e32 v200, v163, v112
	v_fmac_f32_e32 v201, v163, v113
	v_fmac_f32_e32 v200, v164, v113
	v_fmac_f32_e32 v201, v164, v110
	v_fmac_f32_e32 v200, v165, v110
	v_fmac_f32_e32 v201, v165, v111
	v_fmac_f32_e32 v200, v177, v111
	s_waitcnt lgkmcnt(13)
	v_fmac_f32_e32 v201, v177, v108
	v_fmac_f32_e32 v200, v166, v108
	v_fmac_f32_e32 v201, v166, v109
	v_fmac_f32_e32 v200, v167, v109
	s_waitcnt lgkmcnt(12)
	v_fmac_f32_e32 v201, v167, v106
	v_fmac_f32_e32 v200, v168, v106
	v_fmac_f32_e32 v201, v168, v107
	v_fmac_f32_e32 v200, v178, v107
	s_waitcnt lgkmcnt(11)
	v_fmac_f32_e32 v201, v178, v104
	v_fmac_f32_e32 v200, v169, v104
	v_fmac_f32_e32 v201, v169, v105
	v_fmac_f32_e32 v200, v170, v105
	s_waitcnt lgkmcnt(10)
	v_fmac_f32_e32 v201, v170, v102
	v_fmac_f32_e32 v200, v171, v102
	v_fmac_f32_e32 v201, v171, v103
	v_fmac_f32_e32 v200, v179, v103
	s_waitcnt lgkmcnt(9)
	v_fmac_f32_e32 v201, v179, v100
	v_fmac_f32_e32 v200, v180, v100
	v_fmac_f32_e32 v201, v180, v101
	v_fmac_f32_e32 v200, v181, v101
	s_waitcnt lgkmcnt(8)
	v_fmac_f32_e32 v201, v181, v98
	v_fmac_f32_e32 v200, v182, v98
	v_fmac_f32_e32 v201, v182, v99
	v_fmac_f32_e32 v200, v185, v99
	s_waitcnt lgkmcnt(7)
	v_fmac_f32_e32 v201, v185, v94
	v_fmac_f32_e32 v200, v183, v94
	v_fmac_f32_e32 v201, v183, v95
	v_fmac_f32_e32 v200, v184, v95
	s_waitcnt lgkmcnt(6)
; __device__ __forceinline__ void conf_loop(LAS unsigned char* lds, const Params& P, int layer, int first, int nitems, int G, int tid, int lane, int wave) {
;     ...
;             for (int r = 0; r < 8; ++r) { float y = bias;
; #pragma unroll
;                 for (int j = 0; j < 31; ++j) y += w[j] * win[r + j];
;                 YB[(g8 * 8 + r) * 512 + c] = y; }
	v_fmac_f32_e32 v201, v184, v92
	v_fmac_f32_e32 v200, v186, v92
	v_fmac_f32_e32 v201, v186, v93
	ds_write2st64_b32 v133, v200, v201 offset1:8
	v_fma_f32 v200, v172, v202, v187
	v_fmac_f32_e32 v200, v173, v203
	v_fma_f32 v201, v172, v203, v187
	v_fmac_f32_e32 v200, v156, v154
	v_fmac_f32_e32 v201, v173, v154
	v_fma_f32 v154, v172, v154, v187
	v_fmac_f32_e32 v200, v174, v155
	v_fmac_f32_e32 v201, v156, v155
	v_fmac_f32_e32 v154, v173, v155
	v_fma_f32 v155, v172, v155, v187
	v_fmac_f32_e32 v200, v157, v152
	v_fmac_f32_e32 v201, v174, v152
	v_fmac_f32_e32 v154, v156, v152
	v_fmac_f32_e32 v155, v173, v152
	v_fma_f32 v152, v172, v152, v187
	v_fmac_f32_e32 v200, v158, v153
	v_fmac_f32_e32 v201, v157, v153
	v_fmac_f32_e32 v154, v174, v153
	v_fmac_f32_e32 v155, v156, v153
	v_fmac_f32_e32 v152, v173, v153
	v_fma_f32 v153, v172, v153, v187
	v_fmac_f32_e32 v153, v173, v116
	v_fmac_f32_e32 v152, v156, v116
	v_fmac_f32_e32 v153, v156, v117
	v_fmac_f32_e32 v155, v174, v116
	v_fmac_f32_e32 v152, v174, v117
	v_fmac_f32_e32 v153, v174, v114
	v_fmac_f32_e32 v154, v157, v116
	v_fmac_f32_e32 v155, v157, v117
	v_fmac_f32_e32 v152, v157, v114
	v_fmac_f32_e32 v153, v157, v115
	v_fmac_f32_e32 v201, v158, v116
	v_fmac_f32_e32 v154, v158, v117
	v_fmac_f32_e32 v155, v158, v114
	v_fmac_f32_e32 v152, v158, v115
	v_fmac_f32_e32 v153, v158, v112
	v_fmac_f32_e32 v200, v159, v116
	v_fmac_f32_e32 v201, v159, v117
	v_fmac_f32_e32 v154, v159, v114
	v_fmac_f32_e32 v155, v159, v115
	v_fmac_f32_e32 v152, v159, v112
	v_fmac_f32_e32 v153, v159, v113
	v_fmac_f32_e32 v200, v175, v117
	v_fmac_f32_e32 v201, v175, v114
	v_fmac_f32_e32 v154, v175, v115
	v_fmac_f32_e32 v155, v175, v112
	v_fmac_f32_e32 v152, v175, v113
	v_fmac_f32_e32 v153, v175, v110
	v_fmac_f32_e32 v200, v160, v114
	v_fmac_f32_e32 v201, v160, v115
	v_fmac_f32_e32 v154, v160, v112
	v_fmac_f32_e32 v155, v160, v113
	v_fmac_f32_e32 v152, v160, v110
	v_fmac_f32_e32 v153, v160, v111
	v_fmac_f32_e32 v200, v161, v115
	v_fmac_f32_e32 v201, v161, v112
	v_fmac_f32_e32 v154, v161, v113
	v_fmac_f32_e32 v155, v161, v110
	v_fmac_f32_e32 v152, v161, v111
	v_fmac_f32_e32 v153, v161, v108
	v_fmac_f32_e32 v200, v162, v112
	v_fmac_f32_e32 v201, v162, v113
	v_fmac_f32_e32 v154, v162, v110
	v_fmac_f32_e32 v155, v162, v111
	v_fmac_f32_e32 v152, v162, v108
	v_fmac_f32_e32 v153, v162, v109
	v_fmac_f32_e32 v200, v176, v113
	v_fmac_f32_e32 v201, v176, v110
	v_fmac_f32_e32 v154, v176, v111
	v_fmac_f32_e32 v155, v176, v108
	v_fmac_f32_e32 v152, v176, v109
	v_fmac_f32_e32 v153, v176, v106
	v_fmac_f32_e32 v200, v163, v110
	v_fmac_f32_e32 v201, v163, v111
	v_fmac_f32_e32 v154, v163, v108
	v_fmac_f32_e32 v155, v163, v109
	v_fmac_f32_e32 v152, v163, v106
	v_fmac_f32_e32 v153, v163, v107
	v_fmac_f32_e32 v200, v164, v111
	v_fmac_f32_e32 v201, v164, v108
	v_fmac_f32_e32 v154, v164, v109
	v_fmac_f32_e32 v155, v164, v106
	v_fmac_f32_e32 v152, v164, v107
	v_fmac_f32_e32 v153, v164, v104
	v_fmac_f32_e32 v200, v165, v108
	v_fmac_f32_e32 v201, v165, v109
	v_fmac_f32_e32 v154, v165, v106
	v_fmac_f32_e32 v155, v165, v107
	v_fmac_f32_e32 v152, v165, v104
	v_fmac_f32_e32 v153, v165, v105
	v_fmac_f32_e32 v200, v177, v109
	v_fmac_f32_e32 v201, v177, v106
	v_fmac_f32_e32 v154, v177, v107
	v_fmac_f32_e32 v155, v177, v104
	v_fmac_f32_e32 v152, v177, v105
	v_fmac_f32_e32 v153, v177, v102
	v_fmac_f32_e32 v200, v166, v106
	v_fmac_f32_e32 v201, v166, v107
	v_fmac_f32_e32 v154, v166, v104
	v_fmac_f32_e32 v155, v166, v105
	v_fmac_f32_e32 v152, v166, v102
	v_fmac_f32_e32 v153, v166, v103
	v_fmac_f32_e32 v200, v167, v107
	v_fmac_f32_e32 v201, v167, v104
	v_fmac_f32_e32 v154, v167, v105
	v_fmac_f32_e32 v155, v167, v102
	v_fmac_f32_e32 v152, v167, v103
	v_fmac_f32_e32 v153, v167, v100
	v_fmac_f32_e32 v200, v168, v104
	v_fmac_f32_e32 v201, v168, v105
	v_fmac_f32_e32 v154, v168, v102
	v_fmac_f32_e32 v155, v168, v103
	v_fmac_f32_e32 v152, v168, v100
	v_fmac_f32_e32 v153, v168, v101
	v_fmac_f32_e32 v200, v178, v105
	v_fmac_f32_e32 v201, v178, v102
	v_fmac_f32_e32 v154, v178, v103
	v_fmac_f32_e32 v155, v178, v100
	v_fmac_f32_e32 v152, v178, v101
	v_fmac_f32_e32 v153, v178, v98
	v_fmac_f32_e32 v200, v169, v102
	v_fmac_f32_e32 v201, v169, v103
	v_fmac_f32_e32 v154, v169, v100
	v_fmac_f32_e32 v155, v169, v101
	v_fmac_f32_e32 v152, v169, v98
	v_fmac_f32_e32 v153, v169, v99
	v_fmac_f32_e32 v200, v170, v103
	v_fmac_f32_e32 v201, v170, v100
	v_fmac_f32_e32 v154, v170, v101
	v_fmac_f32_e32 v155, v170, v98
	v_fmac_f32_e32 v152, v170, v99
	v_fmac_f32_e32 v153, v170, v94
	v_fmac_f32_e32 v200, v171, v100
	v_fmac_f32_e32 v201, v171, v101
	v_fmac_f32_e32 v154, v171, v98
	v_fmac_f32_e32 v155, v171, v99
	v_fmac_f32_e32 v152, v171, v94
	v_fmac_f32_e32 v153, v171, v95
	v_fmac_f32_e32 v200, v179, v101
	v_fmac_f32_e32 v201, v179, v98
	v_fmac_f32_e32 v154, v179, v99
	v_fmac_f32_e32 v155, v179, v94
	v_fmac_f32_e32 v152, v179, v95
	v_fmac_f32_e32 v153, v179, v92
	v_fmac_f32_e32 v200, v180, v98
	v_fmac_f32_e32 v201, v180, v99
	v_fmac_f32_e32 v154, v180, v94
	v_fmac_f32_e32 v155, v180, v95
	v_fmac_f32_e32 v152, v180, v92
	v_fmac_f32_e32 v153, v180, v93
	v_fmac_f32_e32 v200, v181, v99
	v_fmac_f32_e32 v201, v181, v94
	v_fmac_f32_e32 v154, v181, v95
	v_fmac_f32_e32 v155, v181, v92
	v_fmac_f32_e32 v152, v181, v93
	s_waitcnt lgkmcnt(6)
	v_fmac_f32_e32 v153, v181, v127
	v_fmac_f32_e32 v200, v182, v94
	v_fmac_f32_e32 v201, v182, v95
	v_fmac_f32_e32 v154, v182, v92
	v_fmac_f32_e32 v155, v182, v93
	v_fmac_f32_e32 v152, v182, v127
	s_waitcnt lgkmcnt(5)
	v_fmac_f32_e32 v153, v182, v129
	v_fmac_f32_e32 v200, v185, v95
	v_fmac_f32_e32 v201, v185, v92
	v_fmac_f32_e32 v154, v185, v93
	v_fmac_f32_e32 v155, v185, v127
	v_fmac_f32_e32 v152, v185, v129
	s_waitcnt lgkmcnt(4)
; __device__ __forceinline__ unsigned cvt_pk_bf16(float lo, float hi) { unsigned r; asm volatile("v_cvt_pk_bf16_f32 %0, %1, %2" : "=v"(r) : "v"(lo), "v"(hi)); return r; }
; __device__ __forceinline__ float bflo(unsigned w) { return __uint_as_float(w << 16); }
; __device__ __forceinline__ float bfhi(unsigned w) { return __uint_as_float(w & 0xffff0000u); }
; __device__ __forceinline__ void sconv_finish(const SconvRaw& R, const Params& P, int layer, int r0, int q, int tid) {
;     const int row = r0 + (tid >> 5), c0 = ((tid & 31) + 32 * q) * 8;
;     const int s0 = row < ML ? (row & ~(SEQ - 1)) : ML + ((row - ML) & ~(CTX - 1)), s1 = s0 + (row < ML ? SEQ : CTX);
;     float acc[8];
; #pragma unroll
;     for (int i = 0; i < 8; ++i) acc[i] = 0.f;
; #pragma unroll
;     for (int j = 0; j < 3; ++j) { const int rr = row + j - 1; const float ok = (rr >= s0 && rr < s1) ? 1.0f : 0.0f;
;         const float* wp = P.sc_dw + ((size_t)layer * 3 + j) * 512 + c0; const f32x4 w0 = *(const f32x4*)wp * ok, w1 = *(const f32x4*)(wp + 4) * ok;
;     ...
; #pragma unroll
;         for (int i = 0; i < 4; ++i) { const float wa = i < 2 ? w0[2 * i] : w1[2 * i - 4], wb = i < 2 ? w0[2 * i + 1] : w1[2 * i - 3];
;             acc[2 * i] += wa * bflo(cw[i]) * bflo(hw[i]); acc[2 * i + 1] += wb * bfhi(cw[i]) * bfhi(hw[i]); } }
;     const unsigned bw[4] = {R.bg.x, R.bg.y, R.bg.z, R.bg.w};
;     u32x4 o; unsigned ow[4];
; #pragma unroll
;     for (int i = 0; i < 4; ++i) ow[i] = cvt_pk_bf16(bflo(bw[i]) * acc[2 * i], bfhi(bw[i]) * acc[2 * i + 1]);
;     o.x = ow[0]; o.y = ow[1]; o.z = ow[2]; o.w = ow[3];
;     *(u32x4*)((bf16_t*)(P.ws + WS_MIX) + (size_t)row * DM + 1024 + c0) = o;
; __device__ __forceinline__ void conf_loop(LAS unsigned char* lds, const Params& P, int layer, int first, int nitems, int G, int tid, int lane, int wave) {
;     ...
;                 for (int j = 0; j < 31; ++j) y += w[j] * win[r + j];
;                 YB[(g8 * 8 + r) * 512 + c] = y; }
;             sconv_finish(SR, P, layer, r0, g8, tid);
	v_fmac_f32_e32 v153, v185, v230
	v_fmac_f32_e32 v200, v183, v92
	v_fmac_f32_e32 v201, v183, v93
	v_fmac_f32_e32 v154, v183, v127
	v_fmac_f32_e32 v155, v183, v129
	v_fmac_f32_e32 v152, v183, v230
	s_waitcnt lgkmcnt(3)
	v_fmac_f32_e32 v153, v183, v231
	v_fmac_f32_e32 v200, v184, v93
	v_fmac_f32_e32 v201, v184, v127
	v_fmac_f32_e32 v154, v184, v129
	v_fmac_f32_e32 v155, v184, v230
	v_fmac_f32_e32 v152, v184, v231
	s_waitcnt lgkmcnt(2)
	v_fmac_f32_e32 v153, v184, v232
	v_fmac_f32_e32 v200, v186, v127
	v_fmac_f32_e32 v201, v186, v129
	v_fmac_f32_e32 v154, v186, v230
	v_fmac_f32_e32 v155, v186, v231
	v_fmac_f32_e32 v152, v186, v232
	s_waitcnt lgkmcnt(1)
	v_fmac_f32_e32 v153, v186, v233
	ds_write2st64_b32 v133, v200, v201 offset0:16 offset1:24
	ds_write2st64_b32 v133, v154, v155 offset0:32 offset1:40
	ds_write2st64_b32 v133, v152, v153 offset0:48 offset1:56
	global_load_dwordx4 v[98:101], v[120:121], off
	global_load_dwordx4 v[106:109], v[120:121], off offset:16
	global_load_dwordx4 v[92:95], v[120:121], off offset:2048
	global_load_dwordx4 v[102:105], v[120:121], off offset:2064
	global_load_dwordx4 v[110:113], v[122:123], off
	global_load_dwordx4 v[114:117], v[122:123], off offset:16
	v_cndmask_b32_e64 v134, 0, 1.0, s[18:19]
	s_and_b64 s[18:19], vcc, s[50:51]
	v_cndmask_b32_e64 v132, 0, 1.0, s[18:19]
	s_waitcnt vmcnt(12)
	v_and_b32_e32 v127, 0xffff0000, v78
	s_waitcnt vmcnt(8)
	v_and_b32_e32 v153, 0xffff0000, v82
	v_and_b32_e32 v152, 0xffff0000, v70
	v_lshlrev_b32_e32 v78, 16, v78
	s_mov_b64 s[18:19], 0x269f2800
	s_add_i32 s50, s71, s66
	s_ashr_i32 s51, s50, 31
	s_waitcnt vmcnt(5)
	v_pk_mul_f32 v[100:101], v[134:135], v[100:101] op_sel_hi:[0,1]
	s_waitcnt vmcnt(4)
	v_pk_mul_f32 v[106:107], v[134:135], v[106:107] op_sel_hi:[0,1]
	v_mul_f32_e32 v107, v107, v127
	s_waitcnt vmcnt(2)
	v_pk_mul_f32 v[102:103], v[132:133], v[102:103] op_sel_hi:[0,1]
	v_mov_b32_e32 v154, v103
	s_waitcnt vmcnt(0)
	v_pk_mul_f32 v[114:115], v[130:131], v[114:115] op_sel_hi:[0,1]
	v_mov_b32_e32 v155, v115
	v_and_b32_e32 v127, 0xffff0000, v90
	v_pk_mul_f32 v[152:153], v[154:155], v[152:153]
	v_and_b32_e32 v155, 0xffff0000, v86
	v_and_b32_e32 v154, 0xffff0000, v74
	v_fma_f32 v107, v107, v127, 0
	v_pk_mul_f32 v[152:153], v[152:153], v[154:155]
	v_mul_f32_e32 v78, v106, v78
	v_add_f32_e32 v103, v107, v152
	v_add_f32_e32 v115, v103, v153
	v_lshlrev_b32_e32 v107, 16, v82
	v_lshlrev_b32_e32 v106, 16, v70
	v_mov_b32_e32 v103, v114
	v_lshlrev_b32_e32 v90, 16, v90
	v_pk_mul_f32 v[102:103], v[102:103], v[106:107]
	v_lshlrev_b32_e32 v107, 16, v86
	v_lshlrev_b32_e32 v106, 16, v74
	v_fma_f32 v78, v78, v90, 0
	v_pk_mul_f32 v[102:103], v[102:103], v[106:107]
	v_pk_mul_f32 v[94:95], v[132:133], v[94:95] op_sel_hi:[0,1]
	v_add_f32_e32 v70, v78, v102
	v_pk_mul_f32 v[106:107], v[130:131], v[112:113] op_sel_hi:[0,1]
	v_add_f32_e32 v74, v70, v103
	v_and_b32_e32 v70, 0xffff0000, v77
	v_pk_mul_f32 v[102:103], v[130:131], v[110:111] op_sel_hi:[0,1]
	v_and_b32_e32 v111, 0xffff0000, v81
	v_and_b32_e32 v110, 0xffff0000, v69
	v_mov_b32_e32 v112, v95
	v_mov_b32_e32 v113, v107
	v_mul_f32_e32 v70, v101, v70
	v_and_b32_e32 v78, 0xffff0000, v89
	v_pk_mul_f32 v[110:111], v[112:113], v[110:111]
	v_and_b32_e32 v113, 0xffff0000, v85
	v_and_b32_e32 v112, 0xffff0000, v73
	v_fma_f32 v70, v70, v78, 0
	v_pk_mul_f32 v[110:111], v[110:111], v[112:113]
	v_lshlrev_b32_e32 v101, 16, v81
	v_add_f32_e32 v70, v70, v110
	v_add_f32_e32 v78, v70, v111
	v_lshlrev_b32_e32 v70, 16, v77
	v_mul_f32_e32 v70, v100, v70
	v_lshlrev_b32_e32 v100, 16, v69
	v_mov_b32_e32 v95, v106
	v_lshlrev_b32_e32 v77, 16, v89
	v_pk_mul_f32 v[94:95], v[94:95], v[100:101]
	v_lshlrev_b32_e32 v101, 16, v85
	v_lshlrev_b32_e32 v100, 16, v73
	v_fma_f32 v70, v70, v77, 0
	v_pk_mul_f32 v[94:95], v[94:95], v[100:101]
	v_pk_mul_f32 v[92:93], v[132:133], v[92:93] op_sel_hi:[0,1]
	v_add_f32_e32 v69, v70, v94
	v_pk_mul_f32 v[98:99], v[134:135], v[98:99] op_sel_hi:[0,1]
	v_add_f32_e32 v77, v69, v95
	v_and_b32_e32 v69, 0xffff0000, v76
	v_and_b32_e32 v95, 0xffff0000, v80
	v_and_b32_e32 v94, 0xffff0000, v68
	v_mov_b32_e32 v100, v93
	v_mov_b32_e32 v101, v103
	v_mul_f32_e32 v69, v99, v69
	v_and_b32_e32 v70, 0xffff0000, v88
	v_pk_mul_f32 v[94:95], v[100:101], v[94:95]
	v_and_b32_e32 v101, 0xffff0000, v84
	v_and_b32_e32 v100, 0xffff0000, v72
	v_fma_f32 v69, v69, v70, 0
	v_pk_mul_f32 v[94:95], v[94:95], v[100:101]
	v_lshlrev_b32_e32 v70, 16, v88
	v_add_f32_e32 v69, v69, v94
	v_add_f32_e32 v81, v69, v95
	v_lshlrev_b32_e32 v69, 16, v76
	v_mul_f32_e32 v69, v98, v69
	v_fma_f32 v70, v69, v70, 0
	v_lshlrev_b32_e32 v69, 16, v80
	v_lshlrev_b32_e32 v68, 16, v68
	v_mov_b32_e32 v93, v102
	v_pk_mul_f32 v[68:69], v[92:93], v[68:69]
	v_lshlrev_b32_e32 v73, 16, v84
	v_lshlrev_b32_e32 v72, 16, v72
	v_pk_mul_f32 v[68:69], v[68:69], v[72:73]
	v_pk_mul_f32 v[108:109], v[134:135], v[108:109] op_sel_hi:[0,1]
	v_add_f32_e32 v68, v70, v68
	v_add_f32_e32 v76, v68, v69
	v_and_b32_e32 v68, 0xffff0000, v79
	v_mul_f32_e32 v68, v109, v68
	v_and_b32_e32 v69, 0xffff0000, v91
	v_fma_f32 v80, v68, v69, 0
	v_lshlrev_b32_e32 v68, 16, v79
	v_pk_mul_f32 v[116:117], v[130:131], v[116:117] op_sel_hi:[0,1]
	v_pk_mul_f32 v[104:105], v[132:133], v[104:105] op_sel_hi:[0,1]
	v_mul_f32_e32 v68, v108, v68
	v_lshlrev_b32_e32 v69, 16, v91
	v_fma_f32 v70, v68, v69, 0
	v_lshlrev_b32_e32 v69, 16, v83
	v_lshlrev_b32_e32 v68, 16, v71
	v_mov_b32_e32 v72, v104
	v_mov_b32_e32 v73, v116
	v_pk_mul_f32 v[68:69], v[72:73], v[68:69]
	v_lshlrev_b32_e32 v73, 16, v87
	v_lshlrev_b32_e32 v72, 16, v75
	v_pk_mul_f32 v[68:69], v[68:69], v[72:73]
	v_mov_b32_e32 v116, v105
	v_add_f32_e32 v68, v70, v68
	v_add_f32_e32 v72, v68, v69
; __device__ __forceinline__ unsigned cvt_pk_bf16(float lo, float hi) { unsigned r; asm volatile("v_cvt_pk_bf16_f32 %0, %1, %2" : "=v"(r) : "v"(lo), "v"(hi)); return r; }
; __device__ __forceinline__ float bflo(unsigned w) { return __uint_as_float(w << 16); }
; __device__ __forceinline__ float bfhi(unsigned w) { return __uint_as_float(w & 0xffff0000u); }
; __device__ __forceinline__ void sconv_finish(const SconvRaw& R, const Params& P, int layer, int r0, int q, int tid) {
;     ...
;             acc[2 * i] += wa * bflo(cw[i]) * bflo(hw[i]); acc[2 * i + 1] += wb * bfhi(cw[i]) * bfhi(hw[i]); } }
;     const unsigned bw[4] = {R.bg.x, R.bg.y, R.bg.z, R.bg.w};
;     u32x4 o; unsigned ow[4];
; #pragma unroll
;     for (int i = 0; i < 4; ++i) ow[i] = cvt_pk_bf16(bflo(bw[i]) * acc[2 * i], bfhi(bw[i]) * acc[2 * i + 1]);
;     o.x = ow[0]; o.y = ow[1]; o.z = ow[2]; o.w = ow[3];
;     *(u32x4*)((bf16_t*)(P.ws + WS_MIX) + (size_t)row * DM + 1024 + c0) = o;
; __device__ __forceinline__ void conf_loop(LAS unsigned char* lds, const Params& P, int layer, int first, int nitems, int G, int tid, int lane, int wave) {
;     ...
;             SconvRaw SR; sconv_load(SR, Z, r0, g8, tid);
;             float win[38];
; #pragma unroll
;             for (int i = 0; i < 38; ++i) win[i] = UB[(g8 * 8 + i) * 512 + c];
; #pragma unroll
;             for (int r = 0; r < 8; ++r) { float y = bias;
; #pragma unroll
;                 for (int j = 0; j < 31; ++j) y += w[j] * win[r + j];
	v_and_b32_e32 v69, 0xffff0000, v83
	v_and_b32_e32 v68, 0xffff0000, v71
	v_pk_mul_f32 v[68:69], v[116:117], v[68:69]
	v_and_b32_e32 v71, 0xffff0000, v87
	v_and_b32_e32 v70, 0xffff0000, v75
	v_pk_mul_f32 v[68:69], v[68:69], v[70:71]
	v_mov_b32_e32 v127, v97
	v_add_f32_e32 v68, v80, v68
	v_add_f32_e32 v68, v68, v69
	v_lshlrev_b32_e32 v69, 16, v64
	v_and_b32_e32 v64, 0xffff0000, v64
	v_mul_f32_e32 v69, v76, v69
	v_mul_f32_e32 v64, v81, v64
	v_cvt_pk_bf16_f32 v64, v69, v64
	v_lshlrev_b32_e32 v69, 16, v65
	v_and_b32_e32 v65, 0xffff0000, v65
	v_mul_f32_e32 v69, v77, v69
	v_mul_f32_e32 v65, v78, v65
	v_cvt_pk_bf16_f32 v65, v69, v65
	v_lshlrev_b32_e32 v69, 16, v66
	v_and_b32_e32 v66, 0xffff0000, v66
	v_mul_f32_e32 v69, v74, v69
	v_mul_f32_e32 v66, v115, v66
	v_cvt_pk_bf16_f32 v66, v69, v66
	v_lshlrev_b32_e32 v69, 16, v67
	v_and_b32_e32 v67, 0xffff0000, v67
	v_mul_f32_e32 v69, v72, v69
	v_mul_f32_e32 v67, v68, v67
	v_cvt_pk_bf16_f32 v67, v69, v67
	v_lshl_add_u64 v[68:69], s[68:69], 0, v[150:151]
	v_lshl_add_u64 v[150:151], v[68:69], 0, s[18:19]
	v_lshl_add_u64 v[68:69], v[150:151], 0, v[96:97]
	global_store_dwordx4 v[68:69], v[64:67], off
	s_lshl_b64 s[18:19], s[50:51], 12
	s_add_u32 s18, s68, s18
	v_lshl_add_u64 v[64:65], v[138:139], 0, v[126:127]
	global_load_dwordx4 v[76:79], v[64:65], off
	v_lshl_add_u64 v[64:65], v[136:137], 0, v[126:127]
	global_load_dwordx4 v[88:91], v[64:65], off
	v_lshl_add_u64 v[64:65], v[142:143], 0, v[126:127]
	global_load_dwordx4 v[68:71], v[64:65], off
	v_lshl_add_u64 v[64:65], v[140:141], 0, v[126:127]
	global_load_dwordx4 v[72:75], v[64:65], off
	v_lshl_add_u64 v[64:65], v[148:149], 0, v[126:127]
	global_load_dwordx4 v[80:83], v[64:65], off
	v_lshl_add_u64 v[64:65], v[144:145], 0, v[126:127]
	global_load_dwordx4 v[84:87], v[64:65], off
	v_lshl_add_u64 v[64:65], v[146:147], 0, v[126:127]
	global_load_dwordx4 v[64:67], v[64:65], off
	ds_read2st64_b32 v[114:115], v131 offset0:64 offset1:72
	ds_read2st64_b32 v[116:117], v131 offset0:80 offset1:88
	ds_read2st64_b32 v[112:113], v131 offset0:96 offset1:104
	ds_read2st64_b32 v[110:111], v131 offset0:112 offset1:120
	ds_read2st64_b32 v[108:109], v131 offset0:128 offset1:136
	ds_read2st64_b32 v[106:107], v131 offset0:144 offset1:152
	ds_read2st64_b32 v[104:105], v131 offset0:160 offset1:168
	ds_read2st64_b32 v[102:103], v131 offset0:176 offset1:184
	ds_read2st64_b32 v[100:101], v131 offset0:192 offset1:200
	ds_read2st64_b32 v[98:99], v131 offset0:208 offset1:216
	ds_read2st64_b32 v[94:95], v131 offset0:224 offset1:232
	ds_read2st64_b32 v[92:93], v131 offset0:240 offset1:248
	ds_read_b32 v129, v194
	ds_read_b32 v136, v195
	ds_read_b32 v137, v196
	ds_read_b32 v138, v197
	ds_read_b32 v139, v206
	ds_read_b32 v140, v207
	ds_read_b32 v141, v208
	ds_read_b32 v142, v209
	ds_read_b32 v143, v210
	ds_read_b32 v144, v211
	ds_read_b32 v145, v212
	ds_read_b32 v146, v213
	ds_read_b32 v147, v221
	ds_read_b32 v148, v222
	s_waitcnt lgkmcnt(14)
	v_fma_f32 v114, v172, v114, v187
	v_fmac_f32_e32 v114, v173, v115
	v_fma_f32 v115, v172, v115, v187
	v_fmac_f32_e32 v115, v173, v116
	v_fmac_f32_e32 v114, v156, v116
	v_fmac_f32_e32 v115, v156, v117
	v_fmac_f32_e32 v114, v174, v117
	v_fmac_f32_e32 v115, v174, v112
	v_fmac_f32_e32 v114, v157, v112
	v_fmac_f32_e32 v115, v157, v113
	v_fmac_f32_e32 v114, v158, v113
	v_fmac_f32_e32 v115, v158, v110
	v_fmac_f32_e32 v114, v159, v110
	v_fmac_f32_e32 v115, v159, v111
	v_fmac_f32_e32 v114, v175, v111
	v_fmac_f32_e32 v115, v175, v108
	v_fmac_f32_e32 v114, v160, v108
	v_fmac_f32_e32 v115, v160, v109
	v_fmac_f32_e32 v114, v161, v109
	v_fmac_f32_e32 v115, v161, v106
	v_fmac_f32_e32 v114, v162, v106
	v_fmac_f32_e32 v115, v162, v107
	v_fmac_f32_e32 v114, v176, v107
	v_fmac_f32_e32 v115, v176, v104
	v_fmac_f32_e32 v114, v163, v104
	v_fmac_f32_e32 v115, v163, v105
	v_fmac_f32_e32 v114, v164, v105
	v_fmac_f32_e32 v115, v164, v102
	v_fmac_f32_e32 v114, v165, v102
	v_fmac_f32_e32 v115, v165, v103
	v_fmac_f32_e32 v114, v177, v103
	v_fmac_f32_e32 v115, v177, v100
	v_fmac_f32_e32 v114, v166, v100
	v_fmac_f32_e32 v115, v166, v101
	v_fmac_f32_e32 v114, v167, v101
	v_fmac_f32_e32 v115, v167, v98
	v_fmac_f32_e32 v114, v168, v98
	v_fmac_f32_e32 v115, v168, v99
	v_fmac_f32_e32 v114, v178, v99
	v_fmac_f32_e32 v115, v178, v94
	v_fmac_f32_e32 v114, v169, v94
	v_fmac_f32_e32 v115, v169, v95
	v_fmac_f32_e32 v114, v170, v95
	v_fmac_f32_e32 v115, v170, v92
	v_fmac_f32_e32 v114, v171, v92
	v_fmac_f32_e32 v115, v171, v93
	v_fmac_f32_e32 v114, v179, v93
	s_waitcnt lgkmcnt(13)
	v_fmac_f32_e32 v115, v179, v129
	v_fmac_f32_e32 v114, v180, v129
	s_waitcnt lgkmcnt(12)
	v_fmac_f32_e32 v115, v180, v136
	v_fmac_f32_e32 v114, v181, v136
	s_waitcnt lgkmcnt(11)
	v_fmac_f32_e32 v115, v181, v137
	v_fmac_f32_e32 v114, v182, v137
	s_waitcnt lgkmcnt(10)
	v_fmac_f32_e32 v115, v182, v138
	v_fmac_f32_e32 v114, v185, v138
	s_waitcnt lgkmcnt(9)
	v_fmac_f32_e32 v115, v185, v139
	v_fmac_f32_e32 v114, v183, v139
	s_waitcnt lgkmcnt(8)
	v_fmac_f32_e32 v115, v183, v140
	v_fmac_f32_e32 v114, v184, v140
	s_waitcnt lgkmcnt(7)
	v_fmac_f32_e32 v115, v184, v141
	v_fmac_f32_e32 v114, v186, v141
	s_waitcnt lgkmcnt(6)
; __device__ __forceinline__ void conf_loop(LAS unsigned char* lds, const Params& P, int layer, int first, int nitems, int G, int tid, int lane, int wave) {
;     ...
;             for (int r = 0; r < 8; ++r) { float y = bias;
; #pragma unroll
;                 for (int j = 0; j < 31; ++j) y += w[j] * win[r + j];
;                 YB[(g8 * 8 + r) * 512 + c] = y; }
	v_fmac_f32_e32 v115, v186, v142
	ds_write2st64_b32 v133, v114, v115 offset0:64 offset1:72
	v_fma_f32 v114, v172, v116, v187
	v_fmac_f32_e32 v114, v173, v117
	v_fma_f32 v115, v172, v117, v187
	v_fmac_f32_e32 v114, v156, v112
	v_fmac_f32_e32 v115, v173, v112
	v_fma_f32 v112, v172, v112, v187
	v_fmac_f32_e32 v114, v174, v113
	v_fmac_f32_e32 v115, v156, v113
	v_fmac_f32_e32 v112, v173, v113
	v_fma_f32 v113, v172, v113, v187
	v_fmac_f32_e32 v114, v157, v110
	v_fmac_f32_e32 v115, v174, v110
	v_fmac_f32_e32 v112, v156, v110
	v_fmac_f32_e32 v113, v173, v110
	v_fma_f32 v110, v172, v110, v187
	v_fmac_f32_e32 v114, v158, v111
	v_fmac_f32_e32 v115, v157, v111
	v_fmac_f32_e32 v112, v174, v111
	v_fmac_f32_e32 v113, v156, v111
	v_fmac_f32_e32 v110, v173, v111
	v_fma_f32 v111, v172, v111, v187
	v_fmac_f32_e32 v111, v173, v108
	v_fmac_f32_e32 v110, v156, v108
	v_fmac_f32_e32 v111, v156, v109
	v_fmac_f32_e32 v113, v174, v108
	v_fmac_f32_e32 v110, v174, v109
	v_fmac_f32_e32 v111, v174, v106
	v_fmac_f32_e32 v112, v157, v108
	v_fmac_f32_e32 v113, v157, v109
	v_fmac_f32_e32 v110, v157, v106
	v_fmac_f32_e32 v111, v157, v107
	v_fmac_f32_e32 v115, v158, v108
	v_fmac_f32_e32 v112, v158, v109
	v_fmac_f32_e32 v113, v158, v106
	v_fmac_f32_e32 v110, v158, v107
	v_fmac_f32_e32 v111, v158, v104
	v_fmac_f32_e32 v114, v159, v108
	v_fmac_f32_e32 v115, v159, v109
	v_fmac_f32_e32 v112, v159, v106
	v_fmac_f32_e32 v113, v159, v107
	v_fmac_f32_e32 v110, v159, v104
	v_fmac_f32_e32 v111, v159, v105
	v_fmac_f32_e32 v114, v175, v109
	v_fmac_f32_e32 v115, v175, v106
	v_fmac_f32_e32 v112, v175, v107
	v_fmac_f32_e32 v113, v175, v104
	v_fmac_f32_e32 v110, v175, v105
	v_fmac_f32_e32 v111, v175, v102
	v_fmac_f32_e32 v114, v160, v106
	v_fmac_f32_e32 v115, v160, v107
	v_fmac_f32_e32 v112, v160, v104
	v_fmac_f32_e32 v113, v160, v105
	v_fmac_f32_e32 v110, v160, v102
	v_fmac_f32_e32 v111, v160, v103
	v_fmac_f32_e32 v114, v161, v107
	v_fmac_f32_e32 v115, v161, v104
	v_fmac_f32_e32 v112, v161, v105
	v_fmac_f32_e32 v113, v161, v102
	v_fmac_f32_e32 v110, v161, v103
	v_fmac_f32_e32 v111, v161, v100
	v_fmac_f32_e32 v114, v162, v104
	v_fmac_f32_e32 v115, v162, v105
	v_fmac_f32_e32 v112, v162, v102
	v_fmac_f32_e32 v113, v162, v103
	v_fmac_f32_e32 v110, v162, v100
	v_fmac_f32_e32 v111, v162, v101
	v_fmac_f32_e32 v114, v176, v105
	v_fmac_f32_e32 v115, v176, v102
	v_fmac_f32_e32 v112, v176, v103
	v_fmac_f32_e32 v113, v176, v100
	v_fmac_f32_e32 v110, v176, v101
	v_fmac_f32_e32 v111, v176, v98
	v_fmac_f32_e32 v114, v163, v102
	v_fmac_f32_e32 v115, v163, v103
	v_fmac_f32_e32 v112, v163, v100
	v_fmac_f32_e32 v113, v163, v101
	v_fmac_f32_e32 v110, v163, v98
	v_fmac_f32_e32 v111, v163, v99
	v_fmac_f32_e32 v114, v164, v103
	v_fmac_f32_e32 v115, v164, v100
	v_fmac_f32_e32 v112, v164, v101
	v_fmac_f32_e32 v113, v164, v98
	v_fmac_f32_e32 v110, v164, v99
	v_fmac_f32_e32 v111, v164, v94
	v_fmac_f32_e32 v114, v165, v100
	v_fmac_f32_e32 v115, v165, v101
	v_fmac_f32_e32 v112, v165, v98
	v_fmac_f32_e32 v113, v165, v99
	v_fmac_f32_e32 v110, v165, v94
	v_fmac_f32_e32 v111, v165, v95
	v_fmac_f32_e32 v114, v177, v101
	v_fmac_f32_e32 v115, v177, v98
	v_fmac_f32_e32 v112, v177, v99
	v_fmac_f32_e32 v113, v177, v94
	v_fmac_f32_e32 v110, v177, v95
	v_fmac_f32_e32 v111, v177, v92
	v_fmac_f32_e32 v114, v166, v98
	v_fmac_f32_e32 v115, v166, v99
	v_fmac_f32_e32 v112, v166, v94
	v_fmac_f32_e32 v113, v166, v95
	v_fmac_f32_e32 v110, v166, v92
	v_fmac_f32_e32 v111, v166, v93
	v_fmac_f32_e32 v114, v167, v99
	v_fmac_f32_e32 v115, v167, v94
	v_fmac_f32_e32 v112, v167, v95
	v_fmac_f32_e32 v113, v167, v92
	v_fmac_f32_e32 v110, v167, v93
	v_fmac_f32_e32 v111, v167, v129
	v_fmac_f32_e32 v114, v168, v94
	v_fmac_f32_e32 v115, v168, v95
	v_fmac_f32_e32 v112, v168, v92
	v_fmac_f32_e32 v113, v168, v93
	v_fmac_f32_e32 v110, v168, v129
	v_fmac_f32_e32 v111, v168, v136
	v_fmac_f32_e32 v114, v178, v95
	v_fmac_f32_e32 v115, v178, v92
	v_fmac_f32_e32 v112, v178, v93
	v_fmac_f32_e32 v113, v178, v129
	v_fmac_f32_e32 v110, v178, v136
	v_fmac_f32_e32 v111, v178, v137
	v_fmac_f32_e32 v114, v169, v92
	v_fmac_f32_e32 v115, v169, v93
	v_fmac_f32_e32 v112, v169, v129
	v_fmac_f32_e32 v113, v169, v136
	v_fmac_f32_e32 v110, v169, v137
	v_fmac_f32_e32 v111, v169, v138
	v_fmac_f32_e32 v114, v170, v93
	v_fmac_f32_e32 v115, v170, v129
	v_fmac_f32_e32 v112, v170, v136
	v_fmac_f32_e32 v113, v170, v137
	v_fmac_f32_e32 v110, v170, v138
	v_fmac_f32_e32 v111, v170, v139
	v_fmac_f32_e32 v114, v171, v129
	v_fmac_f32_e32 v115, v171, v136
	v_fmac_f32_e32 v112, v171, v137
	v_fmac_f32_e32 v113, v171, v138
	v_fmac_f32_e32 v110, v171, v139
	v_fmac_f32_e32 v111, v171, v140
	v_fmac_f32_e32 v114, v179, v136
	v_fmac_f32_e32 v115, v179, v137
	v_fmac_f32_e32 v112, v179, v138
	v_fmac_f32_e32 v113, v179, v139
	v_fmac_f32_e32 v110, v179, v140
	v_fmac_f32_e32 v111, v179, v141
	v_fmac_f32_e32 v114, v180, v137
	v_fmac_f32_e32 v115, v180, v138
	v_fmac_f32_e32 v112, v180, v139
	v_fmac_f32_e32 v113, v180, v140
	v_fmac_f32_e32 v110, v180, v141
	v_fmac_f32_e32 v111, v180, v142
	v_fmac_f32_e32 v114, v181, v138
	v_fmac_f32_e32 v115, v181, v139
	v_fmac_f32_e32 v112, v181, v140
	v_fmac_f32_e32 v113, v181, v141
	v_fmac_f32_e32 v110, v181, v142
	s_waitcnt lgkmcnt(6)
	v_fmac_f32_e32 v111, v181, v143
	v_fmac_f32_e32 v114, v182, v139
	v_fmac_f32_e32 v115, v182, v140
	v_fmac_f32_e32 v112, v182, v141
	v_fmac_f32_e32 v113, v182, v142
	v_fmac_f32_e32 v110, v182, v143
	s_waitcnt lgkmcnt(5)
	v_fmac_f32_e32 v111, v182, v144
	v_fmac_f32_e32 v114, v185, v140
	v_fmac_f32_e32 v115, v185, v141
	v_fmac_f32_e32 v112, v185, v142
	v_fmac_f32_e32 v113, v185, v143
	v_fmac_f32_e32 v110, v185, v144
	s_waitcnt lgkmcnt(4)
; __device__ __forceinline__ unsigned cvt_pk_bf16(float lo, float hi) { unsigned r; asm volatile("v_cvt_pk_bf16_f32 %0, %1, %2" : "=v"(r) : "v"(lo), "v"(hi)); return r; }
; __device__ __forceinline__ float bflo(unsigned w) { return __uint_as_float(w << 16); }
; __device__ __forceinline__ float bfhi(unsigned w) { return __uint_as_float(w & 0xffff0000u); }
; __device__ __forceinline__ void sconv_finish(const SconvRaw& R, const Params& P, int layer, int r0, int q, int tid) {
;     const int row = r0 + (tid >> 5), c0 = ((tid & 31) + 32 * q) * 8;
;     const int s0 = row < ML ? (row & ~(SEQ - 1)) : ML + ((row - ML) & ~(CTX - 1)), s1 = s0 + (row < ML ? SEQ : CTX);
;     float acc[8];
; #pragma unroll
;     for (int i = 0; i < 8; ++i) acc[i] = 0.f;
; #pragma unroll
;     for (int j = 0; j < 3; ++j) { const int rr = row + j - 1; const float ok = (rr >= s0 && rr < s1) ? 1.0f : 0.0f;
;         const float* wp = P.sc_dw + ((size_t)layer * 3 + j) * 512 + c0; const f32x4 w0 = *(const f32x4*)wp * ok, w1 = *(const f32x4*)(wp + 4) * ok;
;     ...
; #pragma unroll
;         for (int i = 0; i < 4; ++i) { const float wa = i < 2 ? w0[2 * i] : w1[2 * i - 4], wb = i < 2 ? w0[2 * i + 1] : w1[2 * i - 3];
;             acc[2 * i] += wa * bflo(cw[i]) * bflo(hw[i]); acc[2 * i + 1] += wb * bfhi(cw[i]) * bfhi(hw[i]); } }
;     const unsigned bw[4] = {R.bg.x, R.bg.y, R.bg.z, R.bg.w};
;     u32x4 o; unsigned ow[4];
; #pragma unroll
;     for (int i = 0; i < 4; ++i) ow[i] = cvt_pk_bf16(bflo(bw[i]) * acc[2 * i], bfhi(bw[i]) * acc[2 * i + 1]);
;     o.x = ow[0]; o.y = ow[1]; o.z = ow[2]; o.w = ow[3];
;     *(u32x4*)((bf16_t*)(P.ws + WS_MIX) + (size_t)row * DM + 1024 + c0) = o;
; __device__ __forceinline__ void conf_loop(LAS unsigned char* lds, const Params& P, int layer, int first, int nitems, int G, int tid, int lane, int wave) {
;     ...
;             sconv_finish(SR, P, layer, r0, g8, tid);
;         }
;         __syncthreads();
	v_fmac_f32_e32 v111, v185, v145
	v_fmac_f32_e32 v114, v183, v141
	v_fmac_f32_e32 v115, v183, v142
	v_fmac_f32_e32 v112, v183, v143
	v_fmac_f32_e32 v113, v183, v144
	v_fmac_f32_e32 v110, v183, v145
	s_waitcnt lgkmcnt(3)
	v_fmac_f32_e32 v111, v183, v146
	v_fmac_f32_e32 v114, v184, v142
	v_fmac_f32_e32 v115, v184, v143
	v_fmac_f32_e32 v112, v184, v144
	v_fmac_f32_e32 v113, v184, v145
	v_fmac_f32_e32 v110, v184, v146
	s_waitcnt lgkmcnt(2)
	v_fmac_f32_e32 v111, v184, v147
	v_fmac_f32_e32 v114, v186, v143
	v_fmac_f32_e32 v115, v186, v144
	v_fmac_f32_e32 v112, v186, v145
	v_fmac_f32_e32 v113, v186, v146
	v_fmac_f32_e32 v110, v186, v147
	s_waitcnt lgkmcnt(1)
	v_fmac_f32_e32 v111, v186, v148
	ds_write2st64_b32 v133, v114, v115 offset0:80 offset1:88
	ds_write2st64_b32 v133, v112, v113 offset0:96 offset1:104
	ds_write2st64_b32 v133, v110, v111 offset0:112 offset1:120
	global_load_dwordx4 v[98:101], v[120:121], off offset:1024
	global_load_dwordx4 v[106:109], v[120:121], off offset:1040
	global_load_dwordx4 v[92:95], v[120:121], off offset:3072
	global_load_dwordx4 v[102:105], v[120:121], off offset:3088
	global_load_dwordx4 v[110:113], v[124:125], off
	global_load_dwordx4 v[114:117], v[124:125], off offset:16
	s_waitcnt vmcnt(12)
	v_and_b32_e32 v129, 0xffff0000, v78
	s_waitcnt vmcnt(8)
	v_and_b32_e32 v137, 0xffff0000, v82
	v_and_b32_e32 v136, 0xffff0000, v70
	v_lshlrev_b32_e32 v78, 16, v78
	s_addc_u32 s19, s69, s19
	s_waitcnt vmcnt(5)
	v_pk_mul_f32 v[100:101], v[134:135], v[100:101] op_sel_hi:[0,1]
	s_waitcnt vmcnt(4)
	v_pk_mul_f32 v[106:107], v[134:135], v[106:107] op_sel_hi:[0,1]
	v_mul_f32_e32 v107, v107, v129
	s_waitcnt vmcnt(2)
	v_pk_mul_f32 v[102:103], v[132:133], v[102:103] op_sel_hi:[0,1]
	v_mov_b32_e32 v138, v103
	s_waitcnt vmcnt(0)
	v_pk_mul_f32 v[114:115], v[130:131], v[114:115] op_sel_hi:[0,1]
	v_mov_b32_e32 v139, v115
	v_and_b32_e32 v129, 0xffff0000, v90
	v_pk_mul_f32 v[136:137], v[138:139], v[136:137]
	v_and_b32_e32 v139, 0xffff0000, v86
	v_and_b32_e32 v138, 0xffff0000, v74
	v_fma_f32 v107, v107, v129, 0
	v_pk_mul_f32 v[136:137], v[136:137], v[138:139]
	v_mul_f32_e32 v78, v106, v78
	v_add_f32_e32 v103, v107, v136
	v_add_f32_e32 v115, v103, v137
	v_lshlrev_b32_e32 v107, 16, v82
	v_lshlrev_b32_e32 v106, 16, v70
	v_mov_b32_e32 v103, v114
	v_lshlrev_b32_e32 v90, 16, v90
	v_pk_mul_f32 v[102:103], v[102:103], v[106:107]
	v_lshlrev_b32_e32 v107, 16, v86
	v_lshlrev_b32_e32 v106, 16, v74
	v_fma_f32 v78, v78, v90, 0
	v_pk_mul_f32 v[102:103], v[102:103], v[106:107]
	v_pk_mul_f32 v[94:95], v[132:133], v[94:95] op_sel_hi:[0,1]
	v_add_f32_e32 v70, v78, v102
	v_pk_mul_f32 v[106:107], v[130:131], v[112:113] op_sel_hi:[0,1]
	v_add_f32_e32 v74, v70, v103
	v_and_b32_e32 v70, 0xffff0000, v77
	v_pk_mul_f32 v[102:103], v[130:131], v[110:111] op_sel_hi:[0,1]
	v_and_b32_e32 v111, 0xffff0000, v81
	v_and_b32_e32 v110, 0xffff0000, v69
	v_mov_b32_e32 v112, v95
	v_mov_b32_e32 v113, v107
	v_mul_f32_e32 v70, v101, v70
	v_and_b32_e32 v78, 0xffff0000, v89
	v_pk_mul_f32 v[110:111], v[112:113], v[110:111]
	v_and_b32_e32 v113, 0xffff0000, v85
	v_and_b32_e32 v112, 0xffff0000, v73
	v_fma_f32 v70, v70, v78, 0
	v_pk_mul_f32 v[110:111], v[110:111], v[112:113]
	v_lshlrev_b32_e32 v101, 16, v81
	v_add_f32_e32 v70, v70, v110
	v_add_f32_e32 v78, v70, v111
	v_lshlrev_b32_e32 v70, 16, v77
	v_mul_f32_e32 v70, v100, v70
	v_lshlrev_b32_e32 v100, 16, v69
	v_mov_b32_e32 v95, v106
	v_lshlrev_b32_e32 v77, 16, v89
	v_pk_mul_f32 v[94:95], v[94:95], v[100:101]
	v_lshlrev_b32_e32 v101, 16, v85
	v_lshlrev_b32_e32 v100, 16, v73
	v_fma_f32 v70, v70, v77, 0
	v_pk_mul_f32 v[94:95], v[94:95], v[100:101]
	v_pk_mul_f32 v[92:93], v[132:133], v[92:93] op_sel_hi:[0,1]
	v_add_f32_e32 v69, v70, v94
	v_pk_mul_f32 v[98:99], v[134:135], v[98:99] op_sel_hi:[0,1]
	v_add_f32_e32 v77, v69, v95
	v_and_b32_e32 v69, 0xffff0000, v76
	v_and_b32_e32 v95, 0xffff0000, v80
	v_and_b32_e32 v94, 0xffff0000, v68
	v_mov_b32_e32 v100, v93
	v_mov_b32_e32 v101, v103
	v_mul_f32_e32 v69, v99, v69
	v_and_b32_e32 v70, 0xffff0000, v88
	v_pk_mul_f32 v[94:95], v[100:101], v[94:95]
	v_and_b32_e32 v101, 0xffff0000, v84
	v_and_b32_e32 v100, 0xffff0000, v72
	v_fma_f32 v69, v69, v70, 0
	v_pk_mul_f32 v[94:95], v[94:95], v[100:101]
	v_lshlrev_b32_e32 v70, 16, v88
	v_add_f32_e32 v69, v69, v94
	v_add_f32_e32 v81, v69, v95
	v_lshlrev_b32_e32 v69, 16, v76
	v_mul_f32_e32 v69, v98, v69
	v_fma_f32 v70, v69, v70, 0
	v_lshlrev_b32_e32 v69, 16, v80
	v_lshlrev_b32_e32 v68, 16, v68
	v_mov_b32_e32 v93, v102
	v_pk_mul_f32 v[68:69], v[92:93], v[68:69]
	v_lshlrev_b32_e32 v73, 16, v84
	v_lshlrev_b32_e32 v72, 16, v72
	v_pk_mul_f32 v[68:69], v[68:69], v[72:73]
	v_pk_mul_f32 v[108:109], v[134:135], v[108:109] op_sel_hi:[0,1]
	v_add_f32_e32 v68, v70, v68
	v_add_f32_e32 v76, v68, v69
	v_and_b32_e32 v68, 0xffff0000, v79
	v_mul_f32_e32 v68, v109, v68
	v_and_b32_e32 v69, 0xffff0000, v91
	v_fma_f32 v80, v68, v69, 0
	v_lshlrev_b32_e32 v68, 16, v79
	v_pk_mul_f32 v[116:117], v[130:131], v[116:117] op_sel_hi:[0,1]
	v_pk_mul_f32 v[104:105], v[132:133], v[104:105] op_sel_hi:[0,1]
	v_mul_f32_e32 v68, v108, v68
	v_lshlrev_b32_e32 v69, 16, v91
	v_fma_f32 v70, v68, v69, 0
	v_lshlrev_b32_e32 v69, 16, v83
	v_lshlrev_b32_e32 v68, 16, v71
	v_mov_b32_e32 v72, v104
	v_mov_b32_e32 v73, v116
	v_pk_mul_f32 v[68:69], v[72:73], v[68:69]
	v_lshlrev_b32_e32 v73, 16, v87
	v_lshlrev_b32_e32 v72, 16, v75
	v_pk_mul_f32 v[68:69], v[68:69], v[72:73]
	v_mov_b32_e32 v116, v105
	v_add_f32_e32 v68, v70, v68
	v_add_f32_e32 v72, v68, v69
	v_and_b32_e32 v69, 0xffff0000, v83
	v_and_b32_e32 v68, 0xffff0000, v71
	v_pk_mul_f32 v[68:69], v[116:117], v[68:69]
	v_and_b32_e32 v71, 0xffff0000, v87
	v_and_b32_e32 v70, 0xffff0000, v75
	v_pk_mul_f32 v[68:69], v[68:69], v[70:71]
	v_xor_b32_e32 v70, 32, v215
	v_add_f32_e32 v68, v80, v68
	v_add_f32_e32 v68, v68, v69
	v_lshlrev_b32_e32 v69, 16, v64
	v_and_b32_e32 v64, 0xffff0000, v64
	v_mul_f32_e32 v69, v76, v69
	v_mul_f32_e32 v64, v81, v64
	v_cvt_pk_bf16_f32 v64, v69, v64
	v_lshlrev_b32_e32 v69, 16, v65
	v_and_b32_e32 v65, 0xffff0000, v65
	v_mul_f32_e32 v69, v77, v69
	v_mul_f32_e32 v65, v78, v65
	v_cvt_pk_bf16_f32 v65, v69, v65
	v_lshlrev_b32_e32 v69, 16, v66
	v_and_b32_e32 v66, 0xffff0000, v66
	v_mul_f32_e32 v69, v74, v69
	v_mul_f32_e32 v66, v115, v66
	v_cvt_pk_bf16_f32 v66, v69, v66
	v_lshlrev_b32_e32 v69, 16, v67
	v_and_b32_e32 v67, 0xffff0000, v67
	v_mul_f32_e32 v69, v72, v69
	v_mul_f32_e32 v67, v68, v67
	v_cvt_pk_bf16_f32 v67, v69, v67
	v_lshl_add_u64 v[68:69], v[150:151], 0, v[126:127]
	global_store_dwordx4 v[68:69], v[64:67], off
	v_xor_b32_e32 v68, 8, v215
	v_xor_b32_e32 v69, 16, v215
	v_and_b32_e32 v64, 64, v215
	v_add_u32_e32 v64, 64, v64
	v_xor_b32_e32 v65, 1, v215
	v_cmp_lt_i32_e32 vcc, v65, v64
	v_xor_b32_e32 v66, 2, v215
	v_xor_b32_e32 v67, 4, v215
	v_cndmask_b32_e32 v65, v215, v65, vcc
	v_cmp_lt_i32_e32 vcc, v66, v64
	v_add_u32_e32 v74, s78, v135
	s_waitcnt lgkmcnt(0)
	v_cndmask_b32_e32 v66, v215, v66, vcc
	v_cmp_lt_i32_e32 vcc, v67, v64
	s_barrier
; #define LAS __attribute__((address_space(3)))
; __device__ __forceinline__ unsigned cvt_pk_bf16(float lo, float hi) { unsigned r; asm volatile("v_cvt_pk_bf16_f32 %0, %1, %2" : "=v"(r) : "v"(lo), "v"(hi)); return r; }
; __device__ __forceinline__ float siluf_(float x) { return x * __builtin_amdgcn_rcpf(1.0f + __builtin_amdgcn_exp2f(-1.4426950408889634f * x)); }
; __device__ __forceinline__ float dot4(const f32x4& v) { return (v[0] * v[0] + v[1] * v[1]) + (v[2] * v[2] + v[3] * v[3]); }
; __device__ __forceinline__ float wave_sum(float v) {
; #pragma unroll
;     for (int o = 1; o < 64; o <<= 1) v += __shfl_xor(v, o);
;     return v;
; }
; __device__ __forceinline__ void conf_loop(LAS unsigned char* lds, const Params& P, int layer, int first, int nitems, int G, int tid, int lane, int wave) {
;     ...
;         for (int q = 0; q < 2; ++q) { const int t = 2 * wave + q;
;             f32x4 y0 = *(const LAS f32x4*)(YB + t * 512 + 8 * lane), y1 = *(const LAS f32x4*)(YB + t * 512 + 8 * lane + 4);
;             const float mean = wave_sum((y0[0] + y0[1]) + (y0[2] + y0[3]) + (y1[0] + y1[1]) + (y1[2] + y1[3])) * (1.0f / 512.0f);
;             y0 = y0 - mean; y1 = y1 - mean;
;             const float rstd = rsqrtf(wave_sum(dot4(y0) + dot4(y1)) * (1.0f / 512.0f) + EPS);
;             y0 = y0 * rstd * g0 + b0; y1 = y1 * rstd * g1 + b1;
;             u32x4 o; o.x = cvt_pk_bf16(siluf_(y0[0]), siluf_(y0[1])); o.y = cvt_pk_bf16(siluf_(y0[2]), siluf_(y0[3])); o.z = cvt_pk_bf16(siluf_(y1[0]), siluf_(y1[1])); o.w = cvt_pk_bf16(siluf_(y1[2]), siluf_(y1[3]));
;             *(u32x4*)((bf16_t*)(P.ws + WS_MIX) + (size_t)(r0 + t) * DM + 512 + 8 * lane) = o; }
	s_nop 0
	v_cndmask_b32_e32 v67, v215, v67, vcc
	v_cmp_lt_i32_e32 vcc, v68, v64
	v_lshlrev_b32_e32 v65, 2, v65
	v_lshlrev_b32_e32 v66, 2, v66
	v_cndmask_b32_e32 v68, v215, v68, vcc
	v_cmp_lt_i32_e32 vcc, v69, v64
	v_lshlrev_b32_e32 v67, 2, v67
	v_lshlrev_b32_e32 v68, 2, v68
	v_cndmask_b32_e32 v69, v215, v69, vcc
	v_cmp_lt_i32_e32 vcc, v70, v64
	v_lshlrev_b32_e32 v69, 2, v69
	v_mov_b32_e32 v129, v97
	v_cndmask_b32_e32 v64, v215, v70, vcc
	ds_read_b128 v[70:73], v74
	ds_read_b128 v[74:77], v74 offset:16
	v_lshlrev_b32_e32 v64, 2, v64
	s_waitcnt lgkmcnt(1)
	v_mov_b32_e32 v78, v71
	v_mov_b32_e32 v79, v72
	v_mov_b32_e32 v80, v70
	v_mov_b32_e32 v81, v73
	v_pk_add_f32 v[78:79], v[78:79], v[80:81]
	s_waitcnt lgkmcnt(0)
	v_mov_b32_e32 v80, v76
	v_mov_b32_e32 v81, v74
	v_mov_b32_e32 v82, v77
	v_mov_b32_e32 v83, v75
	v_pk_add_f32 v[80:81], v[80:81], v[82:83]
	v_add_f32_e32 v78, v78, v79
	v_add_f32_e32 v78, v78, v81
	v_add_f32_e32 v78, v80, v78
	s_nop 1
	v_mov_b32_dpp v79, v78 quad_perm:[1,0,3,2] row_mask:0xf bank_mask:0xf
	s_waitcnt lgkmcnt(0)
	v_add_f32_e32 v78, v78, v79
	s_nop 1
	v_mov_b32_dpp v79, v78 quad_perm:[2,3,0,1] row_mask:0xf bank_mask:0xf
	s_waitcnt lgkmcnt(0)
	v_add_f32_e32 v78, v78, v79
	s_nop 1
	v_mov_b32_dpp v79, v78 row_half_mirror row_mask:0xf bank_mask:0xf
	s_waitcnt lgkmcnt(0)
	v_add_f32_e32 v78, v78, v79
	s_nop 1
	v_mov_b32_dpp v79, v78 row_ror:8 row_mask:0xf bank_mask:0xf
	s_waitcnt lgkmcnt(0)
	v_add_f32_e32 v78, v78, v79
	v_mov_b32_e32 v79, v78
	s_nop 1
	v_permlane16_swap_b32_e32 v79, v78
	s_waitcnt lgkmcnt(0)
	v_add_f32_e32 v78, v78, v79
	v_mov_b32_e32 v79, v78
	s_nop 1
	v_permlane32_swap_b32_e32 v79, v78
	s_waitcnt lgkmcnt(0)
	v_add_f32_e32 v78, v78, v79
	v_fmamk_f32 v71, v78, 0xbb000000, v71
	v_fmamk_f32 v75, v78, 0xbb000000, v75
	v_fmamk_f32 v73, v78, 0xbb000000, v73
	v_fmac_f32_e32 v70, 0xbb000000, v78
	v_fmamk_f32 v77, v78, 0xbb000000, v77
	v_fmac_f32_e32 v74, 0xbb000000, v78
	v_mov_b32_e32 v80, v71
	v_mov_b32_e32 v81, v75
	v_fmamk_f32 v72, v78, 0xbb000000, v72
	v_fmamk_f32 v76, v78, 0xbb000000, v76
	v_mov_b32_e32 v78, v70
	v_mov_b32_e32 v79, v74
	v_pk_mul_f32 v[80:81], v[80:81], v[80:81]
	v_mov_b32_e32 v82, v73
	v_mov_b32_e32 v83, v77
	v_pk_fma_f32 v[78:79], v[78:79], v[78:79], v[80:81]
	v_mov_b32_e32 v80, v72
	v_mov_b32_e32 v81, v76
	v_pk_mul_f32 v[82:83], v[82:83], v[82:83]
	s_nop 0
	v_pk_fma_f32 v[80:81], v[80:81], v[80:81], v[82:83]
	s_nop 0
	v_pk_add_f32 v[78:79], v[78:79], v[80:81]
	s_nop 0
	v_add_f32_e32 v78, v78, v79
	s_nop 1
	v_mov_b32_dpp v79, v78 quad_perm:[1,0,3,2] row_mask:0xf bank_mask:0xf
	s_waitcnt lgkmcnt(0)
	v_add_f32_e32 v78, v78, v79
	s_nop 1
	v_mov_b32_dpp v79, v78 quad_perm:[2,3,0,1] row_mask:0xf bank_mask:0xf
	s_waitcnt lgkmcnt(0)
	v_add_f32_e32 v78, v78, v79
	s_nop 1
	v_mov_b32_dpp v79, v78 row_half_mirror row_mask:0xf bank_mask:0xf
	s_waitcnt lgkmcnt(0)
	v_add_f32_e32 v78, v78, v79
	s_nop 1
	v_mov_b32_dpp v79, v78 row_ror:8 row_mask:0xf bank_mask:0xf
	s_waitcnt lgkmcnt(0)
	v_add_f32_e32 v78, v78, v79
	v_mov_b32_e32 v79, v78
	s_nop 1
	v_permlane16_swap_b32_e32 v79, v78
	s_waitcnt lgkmcnt(0)
	v_add_f32_e32 v78, v78, v79
	v_mov_b32_e32 v79, v78
	s_nop 1
	v_permlane32_swap_b32_e32 v79, v78
	s_waitcnt lgkmcnt(0)
	v_add_f32_e32 v78, v78, v79
	v_fmamk_f32 v78, v78, 0x3b000000, v198
	v_cmp_gt_f32_e32 vcc, s33, v78
	v_mul_f32_e32 v79, 0x4b800000, v78
	s_nop 0
	v_cndmask_b32_e32 v78, v78, v79, vcc
	v_rsq_f32_e32 v78, v78
	s_nop 0
	v_mul_f32_e32 v79, 0x45800000, v78
	v_cndmask_b32_e32 v78, v78, v79, vcc
	v_pk_mul_f32 v[70:71], v[70:71], v[78:79] op_sel_hi:[1,0]
	v_pk_mul_f32 v[72:73], v[72:73], v[78:79] op_sel_hi:[1,0]
	v_pk_fma_f32 v[70:71], v[28:29], v[70:71], v[36:37]
	v_pk_mul_f32 v[74:75], v[74:75], v[78:79] op_sel_hi:[1,0]
	v_pk_mul_f32 v[76:77], v[76:77], v[78:79] op_sel_hi:[1,0]
	v_mul_f32_e32 v78, 0xbfb8aa3b, v70
	v_exp_f32_e32 v78, v78
	v_pk_fma_f32 v[72:73], v[30:31], v[72:73], v[38:39]
	v_pk_fma_f32 v[74:75], v[24:25], v[74:75], v[32:33]
	v_pk_fma_f32 v[76:77], v[26:27], v[76:77], v[34:35]
	v_add_f32_e32 v78, 1.0, v78
	v_rcp_f32_e32 v78, v78
	s_nop 0
	v_mul_f32_e32 v70, v70, v78
	v_mul_f32_e32 v78, 0xbfb8aa3b, v71
	v_exp_f32_e32 v78, v78
	s_nop 0
	v_add_f32_e32 v78, 1.0, v78
	v_rcp_f32_e32 v78, v78
	s_nop 0
	v_mul_f32_e32 v71, v71, v78
	v_cvt_pk_bf16_f32 v70, v70, v71
	v_mul_f32_e32 v71, 0xbfb8aa3b, v72
	v_exp_f32_e32 v71, v71
	s_nop 0
	v_add_f32_e32 v71, 1.0, v71
	v_rcp_f32_e32 v71, v71
	s_nop 0
	v_mul_f32_e32 v71, v72, v71
	v_mul_f32_e32 v72, 0xbfb8aa3b, v73
	v_exp_f32_e32 v72, v72
	s_nop 0
	v_add_f32_e32 v72, 1.0, v72
	v_rcp_f32_e32 v72, v72
	s_nop 0
	v_mul_f32_e32 v72, v73, v72
	v_cvt_pk_bf16_f32 v71, v71, v72
	v_mul_f32_e32 v72, 0xbfb8aa3b, v74
	v_mul_f32_e32 v73, 0xbfb8aa3b, v75
	v_exp_f32_e32 v72, v72
	v_exp_f32_e32 v73, v73
	v_add_f32_e32 v72, 1.0, v72
	v_add_f32_e32 v73, 1.0, v73
	v_rcp_f32_e32 v72, v72
	v_rcp_f32_e32 v73, v73
	v_mul_f32_e32 v72, v74, v72
	v_mul_f32_e32 v73, v75, v73
	v_cvt_pk_bf16_f32 v72, v72, v73
	v_mul_f32_e32 v73, 0xbfb8aa3b, v76
	v_mul_f32_e32 v74, 0xbfb8aa3b, v77
	v_exp_f32_e32 v73, v73
	v_exp_f32_e32 v74, v74
	v_add_f32_e32 v73, 1.0, v73
	v_add_f32_e32 v74, 1.0, v74
	v_rcp_f32_e32 v73, v73
	v_rcp_f32_e32 v74, v74
	v_mul_f32_e32 v73, v76, v73
	v_mul_f32_e32 v74, v77, v74
	v_cvt_pk_bf16_f32 v73, v73, v74
	v_lshl_add_u64 v[74:75], s[18:19], 0, v[128:129]
	s_mov_b32 s18, 0x269f2000
	v_add_co_u32_e32 v74, vcc, s18, v74
	s_add_i32 s18, s50, 1
	s_nop 0
	v_addc_co_u32_e32 v75, vcc, 0, v75, vcc
	global_store_dwordx4 v[74:75], v[70:73], off offset:1024
	v_add_u32_e32 v74, s79, v135
	ds_read_b128 v[70:73], v74
	ds_read_b128 v[74:77], v74 offset:16
	s_ashr_i32 s19, s18, 31
	s_lshl_b64 s[18:19], s[18:19], 12
	s_add_u32 s18, s68, s18
	s_waitcnt lgkmcnt(1)
; #define LAS __attribute__((address_space(3)))
; __device__ __forceinline__ unsigned cvt_pk_bf16(float lo, float hi) { unsigned r; asm volatile("v_cvt_pk_bf16_f32 %0, %1, %2" : "=v"(r) : "v"(lo), "v"(hi)); return r; }
; __device__ __forceinline__ float siluf_(float x) { return x * __builtin_amdgcn_rcpf(1.0f + __builtin_amdgcn_exp2f(-1.4426950408889634f * x)); }
; __device__ __forceinline__ float dot4(const f32x4& v) { return (v[0] * v[0] + v[1] * v[1]) + (v[2] * v[2] + v[3] * v[3]); }
; __device__ __forceinline__ float wave_sum(float v) {
; #pragma unroll
;     for (int o = 1; o < 64; o <<= 1) v += __shfl_xor(v, o);
;     return v;
; }
; __device__ __forceinline__ void conf_loop(LAS unsigned char* lds, const Params& P, int layer, int first, int nitems, int G, int tid, int lane, int wave) {
;     ...
;         for (int q = 0; q < 2; ++q) { const int t = 2 * wave + q;
;             f32x4 y0 = *(const LAS f32x4*)(YB + t * 512 + 8 * lane), y1 = *(const LAS f32x4*)(YB + t * 512 + 8 * lane + 4);
;             const float mean = wave_sum((y0[0] + y0[1]) + (y0[2] + y0[3]) + (y1[0] + y1[1]) + (y1[2] + y1[3])) * (1.0f / 512.0f);
;             y0 = y0 - mean; y1 = y1 - mean;
;             const float rstd = rsqrtf(wave_sum(dot4(y0) + dot4(y1)) * (1.0f / 512.0f) + EPS);
;             y0 = y0 * rstd * g0 + b0; y1 = y1 * rstd * g1 + b1;
;             u32x4 o; o.x = cvt_pk_bf16(siluf_(y0[0]), siluf_(y0[1])); o.y = cvt_pk_bf16(siluf_(y0[2]), siluf_(y0[3])); o.z = cvt_pk_bf16(siluf_(y1[0]), siluf_(y1[1])); o.w = cvt_pk_bf16(siluf_(y1[2]), siluf_(y1[3]));
;             *(u32x4*)((bf16_t*)(P.ws + WS_MIX) + (size_t)(r0 + t) * DM + 512 + 8 * lane) = o; }
	v_mov_b32_e32 v78, v71
	v_mov_b32_e32 v79, v72
	v_mov_b32_e32 v80, v70
	v_mov_b32_e32 v81, v73
	v_pk_add_f32 v[78:79], v[78:79], v[80:81]
	s_waitcnt lgkmcnt(0)
	v_mov_b32_e32 v80, v76
	v_mov_b32_e32 v81, v74
	v_mov_b32_e32 v82, v77
	v_mov_b32_e32 v83, v75
	v_pk_add_f32 v[80:81], v[80:81], v[82:83]
	v_add_f32_e32 v78, v78, v79
	v_add_f32_e32 v78, v78, v81
	v_add_f32_e32 v78, v80, v78
	s_nop 1
	v_mov_b32_dpp v79, v78 quad_perm:[1,0,3,2] row_mask:0xf bank_mask:0xf
	s_addc_u32 s19, s69, s19
	s_add_i32 s66, s66, s67
	s_waitcnt lgkmcnt(0)
	v_add_f32_e32 v78, v78, v79
	s_nop 1
	v_mov_b32_dpp v79, v78 quad_perm:[2,3,0,1] row_mask:0xf bank_mask:0xf
	s_waitcnt lgkmcnt(0)
	v_add_f32_e32 v78, v78, v79
	s_nop 1
	v_mov_b32_dpp v79, v78 row_half_mirror row_mask:0xf bank_mask:0xf
	s_waitcnt lgkmcnt(0)
	v_add_f32_e32 v78, v78, v79
	s_nop 1
	v_mov_b32_dpp v79, v78 row_ror:8 row_mask:0xf bank_mask:0xf
	s_waitcnt lgkmcnt(0)
	v_add_f32_e32 v78, v78, v79
	v_mov_b32_e32 v79, v78
	s_nop 1
	v_permlane16_swap_b32_e32 v79, v78
	s_waitcnt lgkmcnt(0)
	v_add_f32_e32 v78, v78, v79
	v_mov_b32_e32 v79, v78
	s_nop 1
	v_permlane32_swap_b32_e32 v79, v78
	s_waitcnt lgkmcnt(0)
	v_add_f32_e32 v78, v78, v79
	v_fmamk_f32 v71, v78, 0xbb000000, v71
	v_fmamk_f32 v75, v78, 0xbb000000, v75
	v_fmamk_f32 v73, v78, 0xbb000000, v73
	v_fmac_f32_e32 v70, 0xbb000000, v78
	v_fmamk_f32 v77, v78, 0xbb000000, v77
	v_fmac_f32_e32 v74, 0xbb000000, v78
	v_mov_b32_e32 v80, v71
	v_mov_b32_e32 v81, v75
	v_fmamk_f32 v72, v78, 0xbb000000, v72
	v_fmamk_f32 v76, v78, 0xbb000000, v76
	v_mov_b32_e32 v78, v70
	v_mov_b32_e32 v79, v74
	v_pk_mul_f32 v[80:81], v[80:81], v[80:81]
	v_mov_b32_e32 v82, v73
	v_mov_b32_e32 v83, v77
	v_pk_fma_f32 v[78:79], v[78:79], v[78:79], v[80:81]
	v_mov_b32_e32 v80, v72
	v_mov_b32_e32 v81, v76
	v_pk_mul_f32 v[82:83], v[82:83], v[82:83]
	s_nop 0
	v_pk_fma_f32 v[80:81], v[80:81], v[80:81], v[82:83]
	s_nop 0
	v_pk_add_f32 v[78:79], v[78:79], v[80:81]
	s_nop 0
	v_add_f32_e32 v78, v78, v79
	s_nop 1
	v_mov_b32_dpp v65, v78 quad_perm:[1,0,3,2] row_mask:0xf bank_mask:0xf
	s_waitcnt lgkmcnt(0)
	v_add_f32_e32 v65, v78, v65
	s_nop 1
	v_mov_b32_dpp v66, v65 quad_perm:[2,3,0,1] row_mask:0xf bank_mask:0xf
	s_waitcnt lgkmcnt(0)
	v_add_f32_e32 v65, v65, v66
	s_nop 1
	v_mov_b32_dpp v66, v65 row_half_mirror row_mask:0xf bank_mask:0xf
	s_waitcnt lgkmcnt(0)
	v_add_f32_e32 v65, v65, v66
	s_nop 1
	v_mov_b32_dpp v66, v65 row_ror:8 row_mask:0xf bank_mask:0xf
	s_waitcnt lgkmcnt(0)
	v_add_f32_e32 v65, v65, v66
	v_mov_b32_e32 v66, v65
	s_nop 1
	v_permlane16_swap_b32_e32 v66, v65
	s_waitcnt lgkmcnt(0)
	v_add_f32_e32 v65, v65, v66
	v_mov_b32_e32 v64, v65
	s_nop 1
	v_permlane32_swap_b32_e32 v64, v65
	s_waitcnt lgkmcnt(0)
	v_add_f32_e32 v64, v65, v64
	v_fmamk_f32 v64, v64, 0x3b000000, v198
	v_cmp_gt_f32_e32 vcc, s33, v64
	v_mul_f32_e32 v65, 0x4b800000, v64
	s_nop 0
	v_cndmask_b32_e32 v64, v64, v65, vcc
	v_rsq_f32_e32 v64, v64
	s_nop 0
	v_mul_f32_e32 v65, 0x45800000, v64
	v_cndmask_b32_e32 v64, v64, v65, vcc
	v_pk_mul_f32 v[66:67], v[70:71], v[64:65] op_sel_hi:[1,0]
	v_pk_mul_f32 v[68:69], v[72:73], v[64:65] op_sel_hi:[1,0]
	v_pk_fma_f32 v[66:67], v[28:29], v[66:67], v[36:37]
	v_pk_mul_f32 v[70:71], v[74:75], v[64:65] op_sel_hi:[1,0]
	v_pk_mul_f32 v[64:65], v[76:77], v[64:65] op_sel_hi:[1,0]
	v_pk_fma_f32 v[68:69], v[30:31], v[68:69], v[38:39]
	v_pk_fma_f32 v[72:73], v[26:27], v[64:65], v[34:35]
	v_mul_f32_e32 v64, 0xbfb8aa3b, v66
	v_mul_f32_e32 v65, 0xbfb8aa3b, v67
	v_exp_f32_e32 v64, v64
	v_exp_f32_e32 v65, v65
	v_pk_fma_f32 v[70:71], v[24:25], v[70:71], v[32:33]
	v_add_f32_e32 v64, 1.0, v64
	v_add_f32_e32 v65, 1.0, v65
	v_rcp_f32_e32 v64, v64
	v_rcp_f32_e32 v65, v65
	v_mul_f32_e32 v64, v66, v64
	v_mul_f32_e32 v65, v67, v65
	v_cvt_pk_bf16_f32 v64, v64, v65
	v_mul_f32_e32 v65, 0xbfb8aa3b, v68
	v_mul_f32_e32 v66, 0xbfb8aa3b, v69
	v_exp_f32_e32 v65, v65
	v_exp_f32_e32 v66, v66
	v_mul_f32_e32 v67, 0xbfb8aa3b, v71
	v_exp_f32_e32 v67, v67
	v_add_f32_e32 v65, 1.0, v65
	v_add_f32_e32 v66, 1.0, v66
	v_rcp_f32_e32 v65, v65
	v_rcp_f32_e32 v66, v66
	v_add_f32_e32 v67, 1.0, v67
	v_rcp_f32_e32 v67, v67
	v_mul_f32_e32 v65, v68, v65
	v_mul_f32_e32 v66, v69, v66
	v_cvt_pk_bf16_f32 v65, v65, v66
	v_mul_f32_e32 v66, 0xbfb8aa3b, v70
	v_exp_f32_e32 v66, v66
	v_mul_f32_e32 v67, v71, v67
	v_mul_f32_e32 v68, 0xbfb8aa3b, v73
	v_exp_f32_e32 v68, v68
	v_add_f32_e32 v66, 1.0, v66
	v_rcp_f32_e32 v66, v66
	v_add_f32_e32 v68, 1.0, v68
	v_rcp_f32_e32 v68, v68
	v_mul_f32_e32 v66, v70, v66
	v_cvt_pk_bf16_f32 v66, v66, v67
	v_mul_f32_e32 v67, 0xbfb8aa3b, v72
	v_exp_f32_e32 v67, v67
	v_mul_f32_e32 v68, v73, v68
	v_add_f32_e32 v67, 1.0, v67
	v_rcp_f32_e32 v67, v67
	s_nop 0
	v_mul_f32_e32 v67, v72, v67
	v_cvt_pk_bf16_f32 v67, v67, v68
	v_lshl_add_u64 v[68:69], s[18:19], 0, v[128:129]
	v_add_co_u32_e32 v68, vcc, 0x269f2000, v68
	s_nop 1
	v_addc_co_u32_e32 v69, vcc, 0, v69, vcc
	s_andn2_b64 vcc, exec, s[64:65]
	global_store_dwordx4 v[68:69], v[64:67], off offset:1024
	s_barrier
	s_cbranch_vccz .LBB0_945

; __device__ __forceinline__ float dot4(const f32x4& v) { return (v[0] * v[0] + v[1] * v[1]) + (v[2] * v[2] + v[3] * v[3]); }
;     __device__ __forceinline__ void fused(f32x4 (&acc)[2][2][4][2], const Unit& u, int wr, int wc, int fr, int fq, PG8_LAS unsigned char* lds, int wid, int lane) const {
;     ...
;         const int row0 = u.pm * BM + wr * 64 + fr, col0 = u.pn * BM + wc * 32 + 4 * fq;
;         const int rb = u.pm < 16 ? 0 : 1;
;         {
;             const float* gp = r.gate + (size_t)rb * 6 * DM + col0;
;             f32x4 gv[2][2];
; #pragma unroll
;             for (int bj = 0; bj < 2; ++bj)
; #pragma unroll
;                 for (int n = 0; n < 2; ++n) gv[bj][n] = *(const f32x4*)(gp + bj * HALF + n * 16);
; #pragma unroll
;             for (int ai = 0; ai < 2; ++ai) {
;                 f32x4 bt[4][2][2];
; #pragma unroll
;                 for (int m = 0; m < 4; ++m) { const float* bp = r.base_lat + (size_t)(row0 + ai * HALF + m * 16) * DM + col0;
; #pragma unroll
;                     for (int bj = 0; bj < 2; ++bj)
; #pragma unroll
;                         for (int n = 0; n < 2; ++n) bt[m][bj][n] = *(const f32x4*)(bp + bj * HALF + n * 16); }
; #pragma unroll
;                 for (int m = 0; m < 4; ++m) {
;                     float sq = 0.f;
; #pragma unroll
;                     for (int bj = 0; bj < 2; ++bj)
; #pragma unroll
;                         for (int n = 0; n < 2; ++n) { const f32x4 x = bt[m][bj][n] + gv[bj][n] * acc[ai][bj][m][n]; acc[ai][bj][m][n] = x; sq += dot4(x); }
;                     sq += __shfl_xor(sq, 16); sq += __shfl_xor(sq, 32);
;                     if (fq == 0) Pt[(ai * HALF + wr * 64 + m * 16 + fr) * 4 + wc] = sq;
;                 }
.LBB0_1084:
	s_mul_i32 s87, s0, 0x24000
	s_add_u32 s1, s44, s87
	s_mul_hi_u32 s86, s0, 0x24000
	s_addc_u32 s18, s45, s86
	s_add_u32 s17, s1, 0x582000
	s_addc_u32 s18, s18, 0
	s_lshl_b32 s1, s48, 8
	s_add_i32 s20, s1, s78
	s_cmp_gt_i32 s48, 15
	v_lshl_or_b32 v96, s50, 8, v140
	s_cselect_b32 s19, 0x3000, 0
	v_or_b32_e32 v208, s88, v96
	s_lshl_b32 s19, s19, 2
	s_add_u32 s24, s17, s19
	v_ashrrev_i32_e32 v209, 31, v208
	s_addc_u32 s25, s18, 0
	v_lshlrev_b64 v[206:207], 2, v[208:209]
	v_lshl_add_u64 v[98:99], s[24:25], 0, v[206:207]
	s_mov_b64 s[24:25], 0x4000
	v_lshl_add_u64 v[134:135], v[98:99], 0, s[24:25]
	s_movk_i32 s24, 0x4000
	v_add_co_u32_e32 v98, vcc, s24, v98
	v_or_b32_e32 v210, s20, v142
	s_nop 0
	v_addc_co_u32_e32 v99, vcc, 0, v99, vcc
	v_ashrrev_i32_e32 v211, 31, v210
	s_waitcnt vmcnt(0)
	s_barrier
	global_load_dwordx4 v[138:141], v[98:99], off
	v_lshl_add_u64 v[212:213], s[46:47], 0, v[206:207]
	v_lshlrev_b64 v[98:99], 13, v[210:211]
	v_lshl_add_u64 v[150:151], v[212:213], 0, v[98:99]
	global_load_dwordx4 v[98:101], v[150:151], off
	global_load_dwordx4 v[200:203], v[150:151], off offset:64
	global_load_dwordx4 v[146:149], v[134:135], off offset:64
	global_load_dwordx4 v[142:145], v[134:135], off offset:512
	global_load_dwordx4 v[224:227], v[150:151], off offset:512
	s_nop 0
	global_load_dwordx4 v[134:137], v[134:135], off offset:576
	s_nop 0
	global_load_dwordx4 v[228:231], v[150:151], off offset:576
	v_or_b32_e32 v150, 16, v210
	v_ashrrev_i32_e32 v151, 31, v150
	v_lshlrev_b64 v[150:151], 13, v[150:151]
	v_lshl_add_u64 v[150:151], v[212:213], 0, v[150:151]
	global_load_dwordx4 v[194:197], v[150:151], off
	global_load_dwordx4 v[190:193], v[150:151], off offset:64
	global_load_dwordx4 v[186:189], v[150:151], off offset:512
	global_load_dwordx4 v[182:185], v[150:151], off offset:576
	v_or_b32_e32 v150, 32, v210
	v_ashrrev_i32_e32 v151, 31, v150
	v_lshlrev_b64 v[150:151], 13, v[150:151]
	v_lshl_add_u64 v[150:151], v[212:213], 0, v[150:151]
	global_load_dwordx4 v[178:181], v[150:151], off
	global_load_dwordx4 v[174:177], v[150:151], off offset:64
	global_load_dwordx4 v[170:173], v[150:151], off offset:512
	global_load_dwordx4 v[166:169], v[150:151], off offset:576
	v_or_b32_e32 v150, 48, v210
	v_ashrrev_i32_e32 v151, 31, v150
	v_lshlrev_b64 v[150:151], 13, v[150:151]
	v_lshl_add_u64 v[150:151], v[212:213], 0, v[150:151]
	global_load_dwordx4 v[162:165], v[150:151], off
	global_load_dwordx4 v[158:161], v[150:151], off offset:64
	global_load_dwordx4 v[154:157], v[150:151], off offset:512
	s_nop 0
	global_load_dwordx4 v[150:153], v[150:151], off offset:576
	v_and_b32_e32 v223, 64, v215
	v_and_b32_e32 v96, 63, v221
	v_xor_b32_e32 v221, 16, v215
	v_add_u32_e32 v223, 64, v223
	v_cmp_lt_i32_e32 vcc, v221, v223
	s_lshl_b32 s20, s23, 2
	s_add_i32 s20, s20, 0
	v_cndmask_b32_e32 v221, v215, v221, vcc
	v_lshlrev_b32_e32 v221, 2, v221
	v_cmp_gt_u32_e64 s[38:39], 16, v96
	s_waitcnt vmcnt(0)
	v_pk_fma_f32 v[94:95], v[94:95], v[140:141], v[100:101]
	v_pk_fma_f32 v[92:93], v[92:93], v[138:139], v[98:99]
	v_pk_fma_f32 v[100:101], v[132:133], v[148:149], v[202:203]
	v_pk_fma_f32 v[98:99], v[130:131], v[146:147], v[200:201]
	v_pk_fma_f32 v[90:91], v[90:91], v[144:145], v[226:227]
	v_pk_fma_f32 v[88:89], v[88:89], v[142:143], v[224:225]
	v_mul_f32_e32 v130, v93, v93
	v_mul_f32_e32 v131, v95, v95
	v_mul_f32_e32 v132, v99, v99
	v_mul_f32_e32 v133, v101, v101
	v_pk_fma_f32 v[86:87], v[86:87], v[136:137], v[230:231]
	v_pk_fma_f32 v[84:85], v[84:85], v[134:135], v[228:229]
	v_mul_f32_e32 v200, v89, v89
	v_mul_f32_e32 v201, v91, v91
	v_fmac_f32_e32 v130, v92, v92
	v_fmac_f32_e32 v131, v94, v94
	v_fmac_f32_e32 v132, v98, v98
	v_fmac_f32_e32 v133, v100, v100
	v_mul_f32_e32 v202, v85, v85
	v_mul_f32_e32 v203, v87, v87
	v_fmac_f32_e32 v200, v88, v88
	v_fmac_f32_e32 v201, v90, v90
	v_add_f32_e32 v130, v130, v131
	v_add_f32_e32 v131, v132, v133
	v_fmac_f32_e32 v202, v84, v84
	v_fmac_f32_e32 v203, v86, v86
	v_add_f32_e32 v132, v200, v201
	v_add_f32_e32 v130, v130, v131
	v_add_f32_e32 v130, v130, v132
	v_add_f32_e32 v131, v202, v203
	v_add_f32_e32 v130, v130, v131
	v_mov_b32_e32 v131, v130
	s_nop 1
	v_permlane16_swap_b32_e32 v131, v130
	v_xor_b32_e32 v132, 32, v215
	v_cmp_lt_i32_e32 vcc, v132, v223
	v_lshl_add_u32 v223, v222, 4, s20
	s_waitcnt lgkmcnt(0)
	v_add_f32_e32 v130, v130, v131
	v_cndmask_b32_e32 v132, v215, v132, vcc
	v_lshlrev_b32_e32 v224, 2, v132
	v_mov_b32_e32 v131, v130
	s_nop 1
	v_permlane32_swap_b32_e32 v131, v130
	s_and_saveexec_b64 s[46:47], s[38:39]
	s_cbranch_execz .LBB0_1086
	s_waitcnt lgkmcnt(0)
	v_add_f32_e32 v130, v130, v131
	ds_write_b32 v223, v130
.LBB0_1086:
	s_or_b64 exec, exec, s[46:47]
	v_pk_fma_f32 v[128:129], v[128:129], v[140:141], v[196:197]
	v_pk_fma_f32 v[126:127], v[126:127], v[138:139], v[194:195]
	s_waitcnt lgkmcnt(0)
	v_mul_f32_e32 v131, v129, v129
	v_mul_f32_e32 v130, v127, v127
	v_fmac_f32_e32 v130, v126, v126
	v_fmac_f32_e32 v131, v128, v128
	v_pk_fma_f32 v[124:125], v[124:125], v[148:149], v[192:193]
	v_pk_fma_f32 v[122:123], v[122:123], v[146:147], v[190:191]
	v_add_f32_e32 v130, v130, v131
	v_mul_f32_e32 v131, v123, v123
	v_mul_f32_e32 v132, v125, v125
	v_fmac_f32_e32 v131, v122, v122
	v_fmac_f32_e32 v132, v124, v124
	v_add_f32_e32 v131, v131, v132
	v_pk_fma_f32 v[116:117], v[116:117], v[144:145], v[188:189]
	v_pk_fma_f32 v[114:115], v[114:115], v[142:143], v[186:187]
	v_add_f32_e32 v130, v130, v131
	v_mul_f32_e32 v131, v115, v115
	v_mul_f32_e32 v132, v117, v117
	v_fmac_f32_e32 v131, v114, v114
	v_fmac_f32_e32 v132, v116, v116
	v_add_f32_e32 v131, v131, v132
	v_pk_fma_f32 v[108:109], v[108:109], v[136:137], v[184:185]
	v_pk_fma_f32 v[106:107], v[106:107], v[134:135], v[182:183]
	v_add_f32_e32 v130, v130, v131
	v_mul_f32_e32 v131, v107, v107
	v_mul_f32_e32 v132, v109, v109
	v_fmac_f32_e32 v131, v106, v106
	v_fmac_f32_e32 v132, v108, v108
	v_add_f32_e32 v131, v131, v132
	v_add_f32_e32 v130, v130, v131
	v_mov_b32_e32 v131, v130
	s_nop 1
	v_permlane16_swap_b32_e32 v131, v130
	s_waitcnt lgkmcnt(0)
	v_add_f32_e32 v130, v130, v131
	v_mov_b32_e32 v131, v130
	s_nop 1
	v_permlane32_swap_b32_e32 v131, v130
	s_and_saveexec_b64 s[46:47], s[38:39]
	s_movk_i32 s90, 0x2000
	s_movk_i32 s89, 0x1000
	s_cbranch_execz .LBB0_1088
	s_waitcnt lgkmcnt(0)
	v_add_f32_e32 v130, v130, v131
	ds_write_b32 v223, v130 offset:256
; __device__ __forceinline__ float dot4(const f32x4& v) { return (v[0] * v[0] + v[1] * v[1]) + (v[2] * v[2] + v[3] * v[3]); }
;     __device__ __forceinline__ void fused(f32x4 (&acc)[2][2][4][2], const Unit& u, int wr, int wc, int fr, int fq, PG8_LAS unsigned char* lds, int wid, int lane) const {
;     ...
;         const int row0 = u.pm * BM + wr * 64 + fr, col0 = u.pn * BM + wc * 32 + 4 * fq;
;         const int rb = u.pm < 16 ? 0 : 1;
;         {
;             const float* gp = r.gate + (size_t)rb * 6 * DM + col0;
;             f32x4 gv[2][2];
; #pragma unroll
;             for (int bj = 0; bj < 2; ++bj)
; #pragma unroll
;                 for (int n = 0; n < 2; ++n) gv[bj][n] = *(const f32x4*)(gp + bj * HALF + n * 16);
; #pragma unroll
;             for (int ai = 0; ai < 2; ++ai) {
;                 f32x4 bt[4][2][2];
; #pragma unroll
;                 for (int m = 0; m < 4; ++m) { const float* bp = r.base_lat + (size_t)(row0 + ai * HALF + m * 16) * DM + col0;
; #pragma unroll
;                     for (int bj = 0; bj < 2; ++bj)
; #pragma unroll
;                         for (int n = 0; n < 2; ++n) bt[m][bj][n] = *(const f32x4*)(bp + bj * HALF + n * 16); }
; #pragma unroll
;                 for (int m = 0; m < 4; ++m) {
;                     float sq = 0.f;
; #pragma unroll
;                     for (int bj = 0; bj < 2; ++bj)
; #pragma unroll
;                         for (int n = 0; n < 2; ++n) { const f32x4 x = bt[m][bj][n] + gv[bj][n] * acc[ai][bj][m][n]; acc[ai][bj][m][n] = x; sq += dot4(x); }
;                     sq += __shfl_xor(sq, 16); sq += __shfl_xor(sq, 32);
;                     if (fq == 0) Pt[(ai * HALF + wr * 64 + m * 16 + fr) * 4 + wc] = sq;
;                 }
.LBB0_1088:
	s_or_b64 exec, exec, s[46:47]
	v_pk_fma_f32 v[120:121], v[120:121], v[140:141], v[180:181]
	v_pk_fma_f32 v[118:119], v[118:119], v[138:139], v[178:179]
	s_waitcnt lgkmcnt(0)
	v_mul_f32_e32 v131, v121, v121
	v_mul_f32_e32 v130, v119, v119
	v_fmac_f32_e32 v130, v118, v118
	v_fmac_f32_e32 v131, v120, v120
	v_pk_fma_f32 v[112:113], v[112:113], v[148:149], v[176:177]
	v_pk_fma_f32 v[110:111], v[110:111], v[146:147], v[174:175]
	v_add_f32_e32 v130, v130, v131
	v_mul_f32_e32 v131, v111, v111
	v_mul_f32_e32 v132, v113, v113
	v_fmac_f32_e32 v131, v110, v110
	v_fmac_f32_e32 v132, v112, v112
	v_add_f32_e32 v131, v131, v132
	v_pk_fma_f32 v[104:105], v[104:105], v[144:145], v[172:173]
	v_pk_fma_f32 v[102:103], v[102:103], v[142:143], v[170:171]
	v_add_f32_e32 v130, v130, v131
	v_mul_f32_e32 v131, v103, v103
	v_mul_f32_e32 v132, v105, v105
	v_fmac_f32_e32 v131, v102, v102
	v_fmac_f32_e32 v132, v104, v104
	v_add_f32_e32 v131, v131, v132
	v_pk_fma_f32 v[82:83], v[82:83], v[136:137], v[168:169]
	v_pk_fma_f32 v[80:81], v[80:81], v[134:135], v[166:167]
	v_add_f32_e32 v130, v130, v131
	v_mul_f32_e32 v131, v81, v81
	v_mul_f32_e32 v132, v83, v83
	v_fmac_f32_e32 v131, v80, v80
	v_fmac_f32_e32 v132, v82, v82
	v_add_f32_e32 v131, v131, v132
	v_add_f32_e32 v130, v130, v131
	v_mov_b32_e32 v131, v130
	s_nop 1
	v_permlane16_swap_b32_e32 v131, v130
	s_waitcnt lgkmcnt(0)
	v_add_f32_e32 v130, v130, v131
	v_mov_b32_e32 v131, v130
	s_nop 1
	v_permlane32_swap_b32_e32 v131, v130
	s_and_saveexec_b64 s[46:47], s[38:39]
	s_cbranch_execz .LBB0_1090
	s_waitcnt lgkmcnt(0)
	v_add_f32_e32 v130, v130, v131
	ds_write_b32 v223, v130 offset:512
.LBB0_1090:
	s_or_b64 exec, exec, s[46:47]
	v_pk_fma_f32 v[78:79], v[78:79], v[140:141], v[164:165]
	v_pk_fma_f32 v[76:77], v[76:77], v[138:139], v[162:163]
	s_waitcnt lgkmcnt(0)
	v_mul_f32_e32 v131, v79, v79
	v_mul_f32_e32 v130, v77, v77
	v_fmac_f32_e32 v130, v76, v76
	v_fmac_f32_e32 v131, v78, v78
	v_pk_fma_f32 v[74:75], v[74:75], v[148:149], v[160:161]
	v_pk_fma_f32 v[72:73], v[72:73], v[146:147], v[158:159]
	v_add_f32_e32 v130, v130, v131
	v_mul_f32_e32 v131, v73, v73
	v_mul_f32_e32 v132, v75, v75
	v_fmac_f32_e32 v131, v72, v72
	v_fmac_f32_e32 v132, v74, v74
	v_add_f32_e32 v131, v131, v132
	v_pk_fma_f32 v[70:71], v[70:71], v[144:145], v[156:157]
	v_pk_fma_f32 v[68:69], v[68:69], v[142:143], v[154:155]
	v_add_f32_e32 v130, v130, v131
	v_mul_f32_e32 v131, v69, v69
	v_mul_f32_e32 v132, v71, v71
	v_fmac_f32_e32 v131, v68, v68
	v_fmac_f32_e32 v132, v70, v70
	v_add_f32_e32 v131, v131, v132
	v_pk_fma_f32 v[66:67], v[66:67], v[136:137], v[152:153]
	v_pk_fma_f32 v[64:65], v[64:65], v[134:135], v[150:151]
	v_add_f32_e32 v130, v130, v131
	v_mul_f32_e32 v131, v65, v65
	v_mul_f32_e32 v132, v67, v67
	v_fmac_f32_e32 v131, v64, v64
	v_fmac_f32_e32 v132, v66, v66
	v_add_f32_e32 v131, v131, v132
	v_add_f32_e32 v130, v130, v131
	v_mov_b32_e32 v131, v130
	s_nop 1
	v_permlane16_swap_b32_e32 v131, v130
	s_waitcnt lgkmcnt(0)
	v_add_f32_e32 v130, v130, v131
	v_mov_b32_e32 v131, v130
	s_nop 1
	v_permlane32_swap_b32_e32 v131, v130
	s_and_saveexec_b64 s[46:47], s[38:39]
	s_cbranch_execz .LBB0_1092
	s_waitcnt lgkmcnt(0)
	v_add_f32_e32 v130, v130, v131
	ds_write_b32 v223, v130 offset:768
.LBB0_1092:
	s_or_b64 exec, exec, s[46:47]
	s_waitcnt lgkmcnt(0)
	v_lshlrev_b64 v[130:131], 13, v[210:211]
	v_lshl_add_u64 v[154:155], v[212:213], 0, v[130:131]
	s_mov_b64 s[24:25], 0x100000
	v_lshl_add_u64 v[130:131], v[154:155], 0, s[24:25]
	v_add_co_u32_e32 v132, vcc, 0x100000, v154
	global_load_dwordx4 v[194:197], v[130:131], off offset:64
	global_load_dwordx4 v[200:203], v[130:131], off offset:512
	v_addc_co_u32_e32 v133, vcc, 0, v155, vcc
	global_load_dwordx4 v[210:213], v[132:133], off
	global_load_dwordx4 v[226:229], v[130:131], off offset:576
	s_mov_b64 s[24:25], 0x120000
	v_lshl_add_u64 v[156:157], v[154:155], 0, s[24:25]
	s_mov_b64 s[24:25], 0x140000
	v_add_co_u32_e32 v160, vcc, 0x120000, v154
	v_lshl_add_u64 v[158:159], v[154:155], 0, s[24:25]
	s_mov_b64 s[24:25], 0x160000
	v_addc_co_u32_e32 v161, vcc, 0, v155, vcc
	v_lshl_add_u64 v[230:231], v[154:155], 0, s[24:25]
	global_load_dwordx4 v[186:189], v[156:157], off offset:64
	global_load_dwordx4 v[178:181], v[156:157], off offset:512
	global_load_dwordx4 v[166:169], v[158:159], off offset:64
	global_load_dwordx4 v[162:165], v[158:159], off offset:512
	global_load_dwordx4 v[150:153], v[230:231], off offset:64
	global_load_dwordx4 v[130:133], v[230:231], off offset:512
	v_add_co_u32_e32 v170, vcc, 0x140000, v154
	global_load_dwordx4 v[190:193], v[160:161], off
	global_load_dwordx4 v[182:185], v[156:157], off offset:576
	v_addc_co_u32_e32 v171, vcc, 0, v155, vcc
	v_add_co_u32_e32 v154, vcc, 0x160000, v154
	global_load_dwordx4 v[174:177], v[170:171], off
	s_nop 0
	global_load_dwordx4 v[170:173], v[158:159], off offset:576
	v_addc_co_u32_e32 v155, vcc, 0, v155, vcc
	global_load_dwordx4 v[158:161], v[154:155], off
	s_nop 0
	global_load_dwordx4 v[154:157], v[230:231], off offset:576
	s_waitcnt vmcnt(15)
	v_pk_fma_f32 v[62:63], v[62:63], v[148:149], v[196:197]
	v_pk_fma_f32 v[60:61], v[60:61], v[146:147], v[194:195]
	s_waitcnt vmcnt(14)
	v_pk_fma_f32 v[54:55], v[54:55], v[144:145], v[202:203]
	v_pk_fma_f32 v[52:53], v[52:53], v[142:143], v[200:201]
	s_waitcnt vmcnt(13)
	v_pk_fma_f32 v[58:59], v[58:59], v[140:141], v[212:213]
	v_pk_fma_f32 v[56:57], v[56:57], v[138:139], v[210:211]
	v_mul_f32_e32 v194, v61, v61
	v_mul_f32_e32 v195, v63, v63
	v_mul_f32_e32 v196, v53, v53
	v_mul_f32_e32 v197, v55, v55
	v_mul_f32_e32 v200, v57, v57
	v_mul_f32_e32 v201, v59, v59
	s_waitcnt vmcnt(12)
	v_pk_fma_f32 v[50:51], v[50:51], v[136:137], v[228:229]
	v_pk_fma_f32 v[48:49], v[48:49], v[134:135], v[226:227]
	v_fmac_f32_e32 v194, v60, v60
	v_fmac_f32_e32 v195, v62, v62
	v_fmac_f32_e32 v196, v52, v52
	v_fmac_f32_e32 v197, v54, v54
	v_fmac_f32_e32 v200, v56, v56
	v_fmac_f32_e32 v201, v58, v58
	v_mul_f32_e32 v202, v49, v49
	v_mul_f32_e32 v203, v51, v51
	v_add_f32_e32 v194, v194, v195
	v_add_f32_e32 v195, v196, v197
	v_add_f32_e32 v196, v200, v201
	v_fmac_f32_e32 v202, v48, v48
	v_fmac_f32_e32 v203, v50, v50
	v_add_f32_e32 v194, v196, v194
	v_add_f32_e32 v194, v194, v195
	v_add_f32_e32 v195, v202, v203
	v_add_f32_e32 v194, v194, v195
	v_mov_b32_e32 v195, v194
	s_nop 1
	v_permlane16_swap_b32_e32 v195, v194
	s_waitcnt lgkmcnt(0)
	v_add_f32_e32 v194, v194, v195
	v_mov_b32_e32 v195, v194
	s_nop 1
	v_permlane32_swap_b32_e32 v195, v194
	s_and_saveexec_b64 s[46:47], s[38:39]
	s_cbranch_execz .LBB0_1094
	s_waitcnt lgkmcnt(0)
	v_add_f32_e32 v194, v194, v195
	ds_write_b32 v223, v194 offset:2048
; __device__ __forceinline__ float dot4(const f32x4& v) { return (v[0] * v[0] + v[1] * v[1]) + (v[2] * v[2] + v[3] * v[3]); }
;     __device__ __forceinline__ void fused(f32x4 (&acc)[2][2][4][2], const Unit& u, int wr, int wc, int fr, int fq, PG8_LAS unsigned char* lds, int wid, int lane) const {
;     ...
;             for (int ai = 0; ai < 2; ++ai) {
;                 f32x4 bt[4][2][2];
; #pragma unroll
;                 for (int m = 0; m < 4; ++m) { const float* bp = r.base_lat + (size_t)(row0 + ai * HALF + m * 16) * DM + col0;
; #pragma unroll
;                     for (int bj = 0; bj < 2; ++bj)
; #pragma unroll
;                         for (int n = 0; n < 2; ++n) bt[m][bj][n] = *(const f32x4*)(bp + bj * HALF + n * 16); }
; #pragma unroll
;                 for (int m = 0; m < 4; ++m) {
;                     float sq = 0.f;
; #pragma unroll
;                     for (int bj = 0; bj < 2; ++bj)
; #pragma unroll
;                         for (int n = 0; n < 2; ++n) { const f32x4 x = bt[m][bj][n] + gv[bj][n] * acc[ai][bj][m][n]; acc[ai][bj][m][n] = x; sq += dot4(x); }
;                     sq += __shfl_xor(sq, 16); sq += __shfl_xor(sq, 32);
;                     if (fq == 0) Pt[(ai * HALF + wr * 64 + m * 16 + fr) * 4 + wc] = sq;
;                 }
.LBB0_1094:
	s_or_b64 exec, exec, s[46:47]
	s_waitcnt vmcnt(5)
	v_pk_fma_f32 v[46:47], v[46:47], v[140:141], v[192:193]
	v_pk_fma_f32 v[44:45], v[44:45], v[138:139], v[190:191]
	v_pk_fma_f32 v[42:43], v[42:43], v[148:149], v[188:189]
	v_pk_fma_f32 v[40:41], v[40:41], v[146:147], v[186:187]
	v_pk_fma_f32 v[38:39], v[38:39], v[144:145], v[180:181]
	v_pk_fma_f32 v[36:37], v[36:37], v[142:143], v[178:179]
	v_mul_f32_e32 v190, v45, v45
	v_mul_f32_e32 v191, v47, v47
	v_mul_f32_e32 v186, v41, v41
	v_mul_f32_e32 v187, v43, v43
	v_mul_f32_e32 v178, v37, v37
	v_mul_f32_e32 v179, v39, v39
	v_fmac_f32_e32 v190, v44, v44
	v_fmac_f32_e32 v191, v46, v46
	v_fmac_f32_e32 v186, v40, v40
	v_fmac_f32_e32 v187, v42, v42
	v_fmac_f32_e32 v178, v36, v36
	v_fmac_f32_e32 v179, v38, v38
	s_waitcnt vmcnt(4)
	v_pk_fma_f32 v[34:35], v[34:35], v[136:137], v[184:185]
	v_pk_fma_f32 v[32:33], v[32:33], v[134:135], v[182:183]
	v_add_f32_e32 v190, v190, v191
	v_add_f32_e32 v186, v186, v187
	v_add_f32_e32 v178, v178, v179
	v_mul_f32_e32 v179, v33, v33
	v_mul_f32_e32 v180, v35, v35
	v_add_f32_e32 v186, v190, v186
	v_fmac_f32_e32 v179, v32, v32
	v_fmac_f32_e32 v180, v34, v34
	v_add_f32_e32 v178, v186, v178
	v_add_f32_e32 v179, v179, v180
	v_add_f32_e32 v178, v178, v179
	v_mov_b32_e32 v179, v178
	s_nop 1
	v_permlane16_swap_b32_e32 v179, v178
	s_waitcnt lgkmcnt(0)
	v_add_f32_e32 v178, v178, v179
	v_mov_b32_e32 v179, v178
	s_nop 1
	v_permlane32_swap_b32_e32 v179, v178
	s_and_saveexec_b64 s[46:47], s[38:39]
	s_cbranch_execz .LBB0_1096
	s_waitcnt lgkmcnt(0)
	v_add_f32_e32 v178, v178, v179
	ds_write_b32 v223, v178 offset:2304
.LBB0_1096:
	s_or_b64 exec, exec, s[46:47]
	s_waitcnt vmcnt(3)
	v_pk_fma_f32 v[30:31], v[30:31], v[140:141], v[176:177]
	v_pk_fma_f32 v[28:29], v[28:29], v[138:139], v[174:175]
	v_pk_fma_f32 v[26:27], v[26:27], v[148:149], v[168:169]
	v_pk_fma_f32 v[24:25], v[24:25], v[146:147], v[166:167]
	v_pk_fma_f32 v[22:23], v[22:23], v[144:145], v[164:165]
	v_pk_fma_f32 v[20:21], v[20:21], v[142:143], v[162:163]
	v_mul_f32_e32 v174, v29, v29
	v_mul_f32_e32 v175, v31, v31
	v_mul_f32_e32 v166, v25, v25
	v_mul_f32_e32 v167, v27, v27
	v_mul_f32_e32 v162, v21, v21
	v_mul_f32_e32 v163, v23, v23
	v_fmac_f32_e32 v174, v28, v28
	v_fmac_f32_e32 v175, v30, v30
	v_fmac_f32_e32 v166, v24, v24
	v_fmac_f32_e32 v167, v26, v26
	v_fmac_f32_e32 v162, v20, v20
	v_fmac_f32_e32 v163, v22, v22
	s_waitcnt vmcnt(2)
	v_pk_fma_f32 v[18:19], v[18:19], v[136:137], v[172:173]
	v_pk_fma_f32 v[16:17], v[16:17], v[134:135], v[170:171]
	v_add_f32_e32 v174, v174, v175
	v_add_f32_e32 v166, v166, v167
	v_add_f32_e32 v162, v162, v163
	v_mul_f32_e32 v163, v17, v17
	v_mul_f32_e32 v164, v19, v19
	v_add_f32_e32 v166, v174, v166
	v_fmac_f32_e32 v163, v16, v16
	v_fmac_f32_e32 v164, v18, v18
	v_add_f32_e32 v162, v166, v162
	v_add_f32_e32 v163, v163, v164
	v_add_f32_e32 v162, v162, v163
	v_mov_b32_e32 v163, v162
	s_nop 1
	v_permlane16_swap_b32_e32 v163, v162
	s_waitcnt lgkmcnt(0)
	v_add_f32_e32 v162, v162, v163
	v_mov_b32_e32 v163, v162
	s_nop 1
	v_permlane32_swap_b32_e32 v163, v162
	s_and_saveexec_b64 s[46:47], s[38:39]
	s_cbranch_execz .LBB0_1098
	s_waitcnt lgkmcnt(0)
	v_add_f32_e32 v162, v162, v163
	ds_write_b32 v223, v162 offset:2560
.LBB0_1098:
	s_or_b64 exec, exec, s[46:47]
	s_waitcnt vmcnt(1)
	v_pk_fma_f32 v[14:15], v[14:15], v[140:141], v[160:161]
	v_pk_fma_f32 v[12:13], v[12:13], v[138:139], v[158:159]
	v_mul_f32_e32 v139, v15, v15
	v_mul_f32_e32 v138, v13, v13
	v_fmac_f32_e32 v138, v12, v12
	v_fmac_f32_e32 v139, v14, v14
	v_pk_fma_f32 v[10:11], v[10:11], v[148:149], v[152:153]
	v_pk_fma_f32 v[8:9], v[8:9], v[146:147], v[150:151]
	v_pk_fma_f32 v[6:7], v[6:7], v[144:145], v[132:133]
	v_pk_fma_f32 v[4:5], v[4:5], v[142:143], v[130:131]
	v_add_f32_e32 v138, v138, v139
	v_mul_f32_e32 v139, v9, v9
	v_mul_f32_e32 v140, v11, v11
	v_mul_f32_e32 v130, v5, v5
	v_mul_f32_e32 v131, v7, v7
	v_fmac_f32_e32 v139, v8, v8
	v_fmac_f32_e32 v140, v10, v10
	v_fmac_f32_e32 v130, v4, v4
	v_fmac_f32_e32 v131, v6, v6
	s_waitcnt vmcnt(0)
	v_pk_fma_f32 v[2:3], v[2:3], v[136:137], v[156:157]
	v_pk_fma_f32 v[0:1], v[0:1], v[134:135], v[154:155]
	v_add_f32_e32 v139, v139, v140
	v_add_f32_e32 v130, v130, v131
	v_mul_f32_e32 v131, v1, v1
	v_mul_f32_e32 v132, v3, v3
	v_add_f32_e32 v138, v138, v139
	v_fmac_f32_e32 v131, v0, v0
	v_fmac_f32_e32 v132, v2, v2
	v_add_f32_e32 v130, v138, v130
	v_add_f32_e32 v131, v131, v132
	v_add_f32_e32 v130, v130, v131
	v_mov_b32_e32 v131, v130
	s_nop 1
	v_permlane16_swap_b32_e32 v131, v130
	s_waitcnt lgkmcnt(0)
	v_add_f32_e32 v130, v130, v131
	v_mov_b32_e32 v131, v130
	s_nop 1
	v_permlane32_swap_b32_e32 v131, v130
	s_and_saveexec_b64 s[46:47], s[38:39]
	s_cbranch_execz .LBB0_1100
	s_waitcnt lgkmcnt(0)
	v_add_f32_e32 v130, v130, v131
	ds_write_b32 v223, v130 offset:2816

; __device__ __forceinline__ float dot4(const f32x4& v) { return (v[0] * v[0] + v[1] * v[1]) + (v[2] * v[2] + v[3] * v[3]); }
;     __device__ __forceinline__ void fused(f32x4 (&acc)[2][2][4][2], const Unit& u, int wr, int wc, int fr, int fq, PG8_LAS unsigned char* lds, int wid, int lane) const {
;     ...
;         const int row0 = u.pm * BM + wr * 64 + fr, col0 = u.pn * BM + wc * 32 + 4 * fq;
;         const int rb = u.pm < 16 ? 0 : 1;
;         {
;             const float* gp = r.gate + (size_t)rb * 6 * DM + col0;
;             f32x4 gv[2][2];
; #pragma unroll
;             for (int bj = 0; bj < 2; ++bj)
; #pragma unroll
;                 for (int n = 0; n < 2; ++n) gv[bj][n] = *(const f32x4*)(gp + bj * HALF + n * 16);
; #pragma unroll
;             for (int ai = 0; ai < 2; ++ai) {
;                 f32x4 bt[4][2][2];
; #pragma unroll
;                 for (int m = 0; m < 4; ++m) { const float* bp = r.base_lat + (size_t)(row0 + ai * HALF + m * 16) * DM + col0;
; #pragma unroll
;                     for (int bj = 0; bj < 2; ++bj)
; #pragma unroll
;                         for (int n = 0; n < 2; ++n) bt[m][bj][n] = *(const f32x4*)(bp + bj * HALF + n * 16); }
; #pragma unroll
;                 for (int m = 0; m < 4; ++m) {
;                     float sq = 0.f;
; #pragma unroll
;                     for (int bj = 0; bj < 2; ++bj)
; #pragma unroll
;                         for (int n = 0; n < 2; ++n) { const f32x4 x = bt[m][bj][n] + gv[bj][n] * acc[ai][bj][m][n]; acc[ai][bj][m][n] = x; sq += dot4(x); }
;                     sq += __shfl_xor(sq, 16); sq += __shfl_xor(sq, 32);
;                     if (fq == 0) Pt[(ai * HALF + wr * 64 + m * 16 + fr) * 4 + wc] = sq;
;                 }
.LBB0_1530:
	s_mul_i32 s17, s0, 0x24000
	s_add_u32 s17, s42, s17
	s_mul_hi_u32 s22, s0, 0x24000
	s_addc_u32 s23, s43, s22
	s_add_u32 s22, s17, 0x582000
	s_addc_u32 s23, s23, 0
	s_add_u32 s40, s42, 0x18cf2000
	s_addc_u32 s41, s43, 0
	s_lshl_b32 s17, s20, 8
	s_add_i32 s25, s17, s85
	s_cmp_gt_i32 s20, 15
	v_lshl_or_b32 v96, s48, 8, v140
	s_cselect_b32 s24, 0x3000, 0
	v_or_b32_e32 v208, s88, v96
	s_lshl_b32 s24, s24, 2
	s_add_u32 s26, s22, s24
	v_ashrrev_i32_e32 v209, 31, v208
	s_addc_u32 s27, s23, 0
	v_lshlrev_b64 v[206:207], 2, v[208:209]
	v_lshl_add_u64 v[98:99], s[26:27], 0, v[206:207]
	s_mov_b64 s[26:27], 0xa000
	v_lshl_add_u64 v[108:109], v[98:99], 0, s[26:27]
	s_mov_b32 s26, 0xa000
	v_add_co_u32_e32 v98, vcc, s26, v98
	v_or_b32_e32 v210, s25, v142
	s_nop 0
	v_addc_co_u32_e32 v99, vcc, 0, v99, vcc
	v_ashrrev_i32_e32 v211, 31, v210
	s_waitcnt vmcnt(0)
	s_barrier
	global_load_dwordx4 v[138:141], v[98:99], off
	v_lshl_add_u64 v[212:213], s[40:41], 0, v[206:207]
	v_lshlrev_b64 v[98:99], 13, v[210:211]
	v_lshl_add_u64 v[98:99], v[212:213], 0, v[98:99]
	global_load_dwordx4 v[200:203], v[98:99], off
	global_load_dwordx4 v[224:227], v[98:99], off offset:64
	global_load_dwordx4 v[146:149], v[108:109], off offset:64
	global_load_dwordx4 v[142:145], v[108:109], off offset:512
	global_load_dwordx4 v[228:231], v[98:99], off offset:512
	global_load_dwordx4 v[134:137], v[108:109], off offset:576
	global_load_dwordx4 v[232:235], v[98:99], off offset:576
	v_or_b32_e32 v98, 16, v210
	v_ashrrev_i32_e32 v99, 31, v98
	v_lshlrev_b64 v[98:99], 13, v[98:99]
	v_lshl_add_u64 v[98:99], v[212:213], 0, v[98:99]
	global_load_dwordx4 v[194:197], v[98:99], off
	global_load_dwordx4 v[190:193], v[98:99], off offset:64
	global_load_dwordx4 v[186:189], v[98:99], off offset:512
	global_load_dwordx4 v[182:185], v[98:99], off offset:576
	v_or_b32_e32 v98, 32, v210
	v_ashrrev_i32_e32 v99, 31, v98
	v_lshlrev_b64 v[98:99], 13, v[98:99]
	v_lshl_add_u64 v[98:99], v[212:213], 0, v[98:99]
	global_load_dwordx4 v[178:181], v[98:99], off
	global_load_dwordx4 v[174:177], v[98:99], off offset:64
	global_load_dwordx4 v[170:173], v[98:99], off offset:512
	global_load_dwordx4 v[166:169], v[98:99], off offset:576
	v_or_b32_e32 v98, 48, v210
	v_ashrrev_i32_e32 v99, 31, v98
	v_lshlrev_b64 v[98:99], 13, v[98:99]
	v_lshl_add_u64 v[98:99], v[212:213], 0, v[98:99]
	global_load_dwordx4 v[162:165], v[98:99], off
	global_load_dwordx4 v[158:161], v[98:99], off offset:64
	global_load_dwordx4 v[154:157], v[98:99], off offset:512
	global_load_dwordx4 v[150:153], v[98:99], off offset:576
	v_and_b32_e32 v99, 64, v215
	v_xor_b32_e32 v98, 16, v215
	v_add_u32_e32 v99, 64, v99
	v_cmp_lt_i32_e32 vcc, v98, v99
	v_and_b32_e32 v96, 63, v221
	s_lshl_b32 s21, s21, 2
	v_cndmask_b32_e32 v98, v215, v98, vcc
	v_lshlrev_b32_e32 v221, 2, v98
	s_add_i32 s21, s21, 0
	v_cmp_gt_u32_e64 s[38:39], 16, v96
	s_waitcnt vmcnt(0)
	v_pk_fma_f32 v[58:59], v[58:59], v[148:149], v[226:227]
	v_pk_fma_f32 v[54:55], v[54:55], v[140:141], v[202:203]
	v_pk_fma_f32 v[52:53], v[52:53], v[138:139], v[200:201]
	v_pk_fma_f32 v[56:57], v[56:57], v[146:147], v[224:225]
	v_pk_fma_f32 v[50:51], v[50:51], v[144:145], v[230:231]
	v_pk_fma_f32 v[48:49], v[48:49], v[142:143], v[228:229]
	v_mul_f32_e32 v98, v53, v53
	v_mul_f32_e32 v108, v55, v55
	v_mul_f32_e32 v109, v57, v57
	v_mul_f32_e32 v200, v59, v59
	v_pk_fma_f32 v[46:47], v[46:47], v[136:137], v[234:235]
	v_pk_fma_f32 v[44:45], v[44:45], v[134:135], v[232:233]
	v_mul_f32_e32 v201, v49, v49
	v_mul_f32_e32 v202, v51, v51
	v_fmac_f32_e32 v98, v52, v52
	v_fmac_f32_e32 v108, v54, v54
	v_fmac_f32_e32 v109, v56, v56
	v_fmac_f32_e32 v200, v58, v58
	v_mul_f32_e32 v203, v45, v45
	v_mul_f32_e32 v223, v47, v47
	v_fmac_f32_e32 v201, v48, v48
	v_fmac_f32_e32 v202, v50, v50
	v_add_f32_e32 v98, v98, v108
	v_add_f32_e32 v108, v109, v200
	v_fmac_f32_e32 v203, v44, v44
	v_fmac_f32_e32 v223, v46, v46
	v_add_f32_e32 v109, v201, v202
	v_add_f32_e32 v98, v98, v108
	v_add_f32_e32 v98, v98, v109
	v_add_f32_e32 v108, v203, v223
	v_add_f32_e32 v98, v98, v108
	v_mov_b32_e32 v108, v98
	s_nop 1
	v_permlane16_swap_b32_e32 v108, v98
	v_xor_b32_e32 v109, 32, v215
	v_cmp_lt_i32_e32 vcc, v109, v99
	v_lshl_add_u32 v223, v222, 4, s21
	s_waitcnt lgkmcnt(0)
	v_add_f32_e32 v98, v98, v108
	v_cndmask_b32_e32 v99, v215, v109, vcc
	v_lshlrev_b32_e32 v224, 2, v99
	v_mov_b32_e32 v99, v98
	s_nop 1
	v_permlane32_swap_b32_e32 v99, v98
	s_and_saveexec_b64 s[50:51], s[38:39]
	s_cbranch_execz .LBB0_1532
	s_waitcnt lgkmcnt(0)
	v_add_f32_e32 v98, v98, v99
	ds_write_b32 v223, v98
.LBB0_1532:
	s_or_b64 exec, exec, s[50:51]
	v_pk_fma_f32 v[108:109], v[106:107], v[140:141], v[196:197]
	v_pk_fma_f32 v[106:107], v[104:105], v[138:139], v[194:195]
	s_waitcnt lgkmcnt(0)
	v_mul_f32_e32 v99, v109, v109
	v_mul_f32_e32 v98, v107, v107
	v_fmac_f32_e32 v98, v106, v106
	v_fmac_f32_e32 v99, v108, v108
	v_pk_fma_f32 v[86:87], v[86:87], v[148:149], v[192:193]
	v_pk_fma_f32 v[84:85], v[84:85], v[146:147], v[190:191]
	v_add_f32_e32 v98, v98, v99
	v_mul_f32_e32 v99, v85, v85
	v_mul_f32_e32 v104, v87, v87
	v_fmac_f32_e32 v99, v84, v84
	v_fmac_f32_e32 v104, v86, v86
	v_add_f32_e32 v99, v99, v104
	v_pk_fma_f32 v[78:79], v[78:79], v[144:145], v[188:189]
	v_pk_fma_f32 v[76:77], v[76:77], v[142:143], v[186:187]
	v_add_f32_e32 v98, v98, v99
	v_mul_f32_e32 v99, v77, v77
	v_mul_f32_e32 v104, v79, v79
	v_fmac_f32_e32 v99, v76, v76
	v_fmac_f32_e32 v104, v78, v78
	v_add_f32_e32 v99, v99, v104
	v_pk_fma_f32 v[70:71], v[70:71], v[136:137], v[184:185]
	v_pk_fma_f32 v[68:69], v[68:69], v[134:135], v[182:183]
	v_add_f32_e32 v98, v98, v99
	v_mul_f32_e32 v99, v69, v69
	v_mul_f32_e32 v104, v71, v71
	v_fmac_f32_e32 v99, v68, v68
	v_fmac_f32_e32 v104, v70, v70
	v_add_f32_e32 v99, v99, v104
	v_add_f32_e32 v98, v98, v99
	v_mov_b32_e32 v99, v98
	s_nop 1
	v_permlane16_swap_b32_e32 v99, v98
	s_waitcnt lgkmcnt(0)
	v_add_f32_e32 v98, v98, v99
	v_mov_b32_e32 v99, v98
	s_nop 1
	v_permlane32_swap_b32_e32 v99, v98
	s_and_saveexec_b64 s[50:51], s[38:39]
	v_readlane_b32 s78, v255, 48
	v_readlane_b32 s54, v255, 50
	s_movk_i32 s90, 0x2000
	s_movk_i32 s89, 0x1000
	v_readlane_b32 s79, v255, 49
	v_readlane_b32 s55, v255, 51
	s_cbranch_execz .LBB0_1534
	s_waitcnt lgkmcnt(0)
	v_add_f32_e32 v98, v98, v99
	ds_write_b32 v223, v98 offset:256
; __device__ __forceinline__ float dot4(const f32x4& v) { return (v[0] * v[0] + v[1] * v[1]) + (v[2] * v[2] + v[3] * v[3]); }
;     __device__ __forceinline__ void fused(f32x4 (&acc)[2][2][4][2], const Unit& u, int wr, int wc, int fr, int fq, PG8_LAS unsigned char* lds, int wid, int lane) const {
;     ...
;             for (int ai = 0; ai < 2; ++ai) {
;                 f32x4 bt[4][2][2];
; #pragma unroll
;                 for (int m = 0; m < 4; ++m) { const float* bp = r.base_lat + (size_t)(row0 + ai * HALF + m * 16) * DM + col0;
; #pragma unroll
;                     for (int bj = 0; bj < 2; ++bj)
; #pragma unroll
;                         for (int n = 0; n < 2; ++n) bt[m][bj][n] = *(const f32x4*)(bp + bj * HALF + n * 16); }
; #pragma unroll
;                 for (int m = 0; m < 4; ++m) {
;                     float sq = 0.f;
; #pragma unroll
;                     for (int bj = 0; bj < 2; ++bj)
; #pragma unroll
;                         for (int n = 0; n < 2; ++n) { const f32x4 x = bt[m][bj][n] + gv[bj][n] * acc[ai][bj][m][n]; acc[ai][bj][m][n] = x; sq += dot4(x); }
;                     sq += __shfl_xor(sq, 16); sq += __shfl_xor(sq, 32);
;                     if (fq == 0) Pt[(ai * HALF + wr * 64 + m * 16 + fr) * 4 + wc] = sq;
;                 }
.LBB0_1534:
	s_or_b64 exec, exec, s[50:51]
	v_pk_fma_f32 v[112:113], v[112:113], v[140:141], v[180:181]
	v_pk_fma_f32 v[110:111], v[110:111], v[138:139], v[178:179]
	s_waitcnt lgkmcnt(0)
	v_mul_f32_e32 v99, v113, v113
	v_mul_f32_e32 v98, v111, v111
	v_fmac_f32_e32 v98, v110, v110
	v_fmac_f32_e32 v99, v112, v112
	v_pk_fma_f32 v[104:105], v[102:103], v[148:149], v[176:177]
	v_pk_fma_f32 v[102:103], v[100:101], v[146:147], v[174:175]
	v_add_f32_e32 v98, v98, v99
	v_mul_f32_e32 v99, v103, v103
	v_mul_f32_e32 v100, v105, v105
	v_fmac_f32_e32 v99, v102, v102
	v_fmac_f32_e32 v100, v104, v104
	v_add_f32_e32 v99, v99, v100
	v_add_f32_e32 v174, v98, v99
	v_pk_fma_f32 v[100:101], v[132:133], v[144:145], v[172:173]
	v_pk_fma_f32 v[98:99], v[130:131], v[142:143], v[170:171]
	v_mul_f32_e32 v131, v101, v101
	v_mul_f32_e32 v130, v99, v99
	v_fmac_f32_e32 v130, v98, v98
	v_fmac_f32_e32 v131, v100, v100
	v_pk_fma_f32 v[94:95], v[94:95], v[136:137], v[168:169]
	v_pk_fma_f32 v[92:93], v[92:93], v[134:135], v[166:167]
	v_add_f32_e32 v130, v130, v131
	v_mul_f32_e32 v131, v93, v93
	v_mul_f32_e32 v132, v95, v95
	v_fmac_f32_e32 v131, v92, v92
	v_fmac_f32_e32 v132, v94, v94
	v_add_f32_e32 v130, v174, v130
	v_add_f32_e32 v131, v131, v132
	v_add_f32_e32 v130, v130, v131
	v_mov_b32_e32 v131, v130
	s_nop 1
	v_permlane16_swap_b32_e32 v131, v130
	s_waitcnt lgkmcnt(0)
	v_add_f32_e32 v130, v130, v131
	v_mov_b32_e32 v131, v130
	s_nop 1
	v_permlane32_swap_b32_e32 v131, v130
	s_and_saveexec_b64 s[50:51], s[38:39]
	s_cbranch_execz .LBB0_1536
	s_waitcnt lgkmcnt(0)
	v_add_f32_e32 v130, v130, v131
	ds_write_b32 v223, v130 offset:512
.LBB0_1536:
	s_or_b64 exec, exec, s[50:51]
	v_pk_fma_f32 v[90:91], v[90:91], v[140:141], v[164:165]
	v_pk_fma_f32 v[88:89], v[88:89], v[138:139], v[162:163]
	s_waitcnt lgkmcnt(0)
	v_mul_f32_e32 v131, v91, v91
	v_mul_f32_e32 v130, v89, v89
	v_fmac_f32_e32 v130, v88, v88
	v_fmac_f32_e32 v131, v90, v90
	v_pk_fma_f32 v[82:83], v[82:83], v[148:149], v[160:161]
	v_pk_fma_f32 v[80:81], v[80:81], v[146:147], v[158:159]
	v_add_f32_e32 v130, v130, v131
	v_mul_f32_e32 v131, v81, v81
	v_mul_f32_e32 v132, v83, v83
	v_fmac_f32_e32 v131, v80, v80
	v_fmac_f32_e32 v132, v82, v82
	v_add_f32_e32 v131, v131, v132
	v_pk_fma_f32 v[74:75], v[74:75], v[144:145], v[156:157]
	v_pk_fma_f32 v[72:73], v[72:73], v[142:143], v[154:155]
	v_add_f32_e32 v130, v130, v131
	v_mul_f32_e32 v131, v73, v73
	v_mul_f32_e32 v132, v75, v75
	v_fmac_f32_e32 v131, v72, v72
	v_fmac_f32_e32 v132, v74, v74
	v_add_f32_e32 v131, v131, v132
	v_pk_fma_f32 v[66:67], v[66:67], v[136:137], v[152:153]
	v_pk_fma_f32 v[64:65], v[64:65], v[134:135], v[150:151]
	v_add_f32_e32 v130, v130, v131
	v_mul_f32_e32 v131, v65, v65
	v_mul_f32_e32 v132, v67, v67
	v_fmac_f32_e32 v131, v64, v64
	v_fmac_f32_e32 v132, v66, v66
	v_add_f32_e32 v131, v131, v132
	v_add_f32_e32 v130, v130, v131
	v_mov_b32_e32 v131, v130
	s_nop 1
	v_permlane16_swap_b32_e32 v131, v130
	s_waitcnt lgkmcnt(0)
	v_add_f32_e32 v130, v130, v131
	v_mov_b32_e32 v131, v130
	s_nop 1
	v_permlane32_swap_b32_e32 v131, v130
	s_and_saveexec_b64 s[50:51], s[38:39]
	s_cbranch_execz .LBB0_1538
	s_waitcnt lgkmcnt(0)
	v_add_f32_e32 v130, v130, v131
	ds_write_b32 v223, v130 offset:768
.LBB0_1538:
	s_or_b64 exec, exec, s[50:51]
	s_waitcnt lgkmcnt(0)
	v_lshlrev_b64 v[130:131], 13, v[210:211]
	v_lshl_add_u64 v[154:155], v[212:213], 0, v[130:131]
	s_mov_b64 s[26:27], 0x100000
	v_lshl_add_u64 v[130:131], v[154:155], 0, s[26:27]
	v_add_co_u32_e32 v132, vcc, 0x100000, v154
	global_load_dwordx4 v[194:197], v[130:131], off offset:64
	global_load_dwordx4 v[200:203], v[130:131], off offset:512
	v_addc_co_u32_e32 v133, vcc, 0, v155, vcc
	global_load_dwordx4 v[210:213], v[132:133], off
	global_load_dwordx4 v[226:229], v[130:131], off offset:576
	s_mov_b64 s[26:27], 0x120000
	v_lshl_add_u64 v[156:157], v[154:155], 0, s[26:27]
	s_mov_b64 s[26:27], 0x140000
	v_add_co_u32_e32 v160, vcc, 0x120000, v154
	v_lshl_add_u64 v[158:159], v[154:155], 0, s[26:27]
	s_mov_b64 s[26:27], 0x160000
	v_addc_co_u32_e32 v161, vcc, 0, v155, vcc
	v_lshl_add_u64 v[230:231], v[154:155], 0, s[26:27]
	global_load_dwordx4 v[186:189], v[156:157], off offset:64
	global_load_dwordx4 v[178:181], v[156:157], off offset:512
	global_load_dwordx4 v[166:169], v[158:159], off offset:64
	global_load_dwordx4 v[162:165], v[158:159], off offset:512
	global_load_dwordx4 v[150:153], v[230:231], off offset:64
	global_load_dwordx4 v[130:133], v[230:231], off offset:512
	v_add_co_u32_e32 v170, vcc, 0x140000, v154
	global_load_dwordx4 v[190:193], v[160:161], off
	global_load_dwordx4 v[182:185], v[156:157], off offset:576
	v_addc_co_u32_e32 v171, vcc, 0, v155, vcc
	v_add_co_u32_e32 v154, vcc, 0x160000, v154
	global_load_dwordx4 v[174:177], v[170:171], off
	s_nop 0
	global_load_dwordx4 v[170:173], v[158:159], off offset:576
	v_addc_co_u32_e32 v155, vcc, 0, v155, vcc
	global_load_dwordx4 v[158:161], v[154:155], off
	s_nop 0
	global_load_dwordx4 v[154:157], v[230:231], off offset:576
	s_waitcnt vmcnt(15)
	v_pk_fma_f32 v[124:125], v[124:125], v[148:149], v[196:197]
	v_pk_fma_f32 v[122:123], v[122:123], v[146:147], v[194:195]
	s_waitcnt vmcnt(14)
	v_pk_fma_f32 v[120:121], v[120:121], v[144:145], v[202:203]
	v_pk_fma_f32 v[118:119], v[118:119], v[142:143], v[200:201]
	s_waitcnt vmcnt(13)
	v_pk_fma_f32 v[128:129], v[128:129], v[140:141], v[212:213]
	v_pk_fma_f32 v[126:127], v[126:127], v[138:139], v[210:211]
	v_mul_f32_e32 v194, v123, v123
	v_mul_f32_e32 v195, v125, v125
	v_mul_f32_e32 v196, v119, v119
	v_mul_f32_e32 v197, v121, v121
	v_mul_f32_e32 v200, v127, v127
	v_mul_f32_e32 v201, v129, v129
	s_waitcnt vmcnt(12)
	v_pk_fma_f32 v[116:117], v[116:117], v[136:137], v[228:229]
	v_pk_fma_f32 v[114:115], v[114:115], v[134:135], v[226:227]
	v_fmac_f32_e32 v194, v122, v122
	v_fmac_f32_e32 v195, v124, v124
	v_fmac_f32_e32 v196, v118, v118
	v_fmac_f32_e32 v197, v120, v120
	v_fmac_f32_e32 v200, v126, v126
	v_fmac_f32_e32 v201, v128, v128
	v_mul_f32_e32 v202, v115, v115
	v_mul_f32_e32 v203, v117, v117
	v_add_f32_e32 v194, v194, v195
	v_add_f32_e32 v195, v196, v197
	v_add_f32_e32 v196, v200, v201
	v_fmac_f32_e32 v202, v114, v114
	v_fmac_f32_e32 v203, v116, v116
	v_add_f32_e32 v194, v196, v194
	v_add_f32_e32 v194, v194, v195
	v_add_f32_e32 v195, v202, v203
	v_add_f32_e32 v194, v194, v195
	v_mov_b32_e32 v195, v194
	s_nop 1
	v_permlane16_swap_b32_e32 v195, v194
	s_waitcnt lgkmcnt(0)
	v_add_f32_e32 v194, v194, v195
	v_mov_b32_e32 v195, v194
	s_nop 1
	v_permlane32_swap_b32_e32 v195, v194
	s_and_saveexec_b64 s[50:51], s[38:39]
	s_cbranch_execz .LBB0_1540
	s_waitcnt lgkmcnt(0)
	v_add_f32_e32 v194, v194, v195
	ds_write_b32 v223, v194 offset:2048
; __device__ __forceinline__ float dot4(const f32x4& v) { return (v[0] * v[0] + v[1] * v[1]) + (v[2] * v[2] + v[3] * v[3]); }
;     __device__ __forceinline__ void fused(f32x4 (&acc)[2][2][4][2], const Unit& u, int wr, int wc, int fr, int fq, PG8_LAS unsigned char* lds, int wid, int lane) const {
;     ...
;                 for (int m = 0; m < 4; ++m) {
;                     float sq = 0.f;
; #pragma unroll
;                     for (int bj = 0; bj < 2; ++bj)
; #pragma unroll
;                         for (int n = 0; n < 2; ++n) { const f32x4 x = bt[m][bj][n] + gv[bj][n] * acc[ai][bj][m][n]; acc[ai][bj][m][n] = x; sq += dot4(x); }
;                     sq += __shfl_xor(sq, 16); sq += __shfl_xor(sq, 32);
;                     if (fq == 0) Pt[(ai * HALF + wr * 64 + m * 16 + fr) * 4 + wc] = sq;
;                 }
.LBB0_1540:
	s_or_b64 exec, exec, s[50:51]
	s_waitcnt vmcnt(5)
	v_pk_fma_f32 v[62:63], v[62:63], v[140:141], v[192:193]
	v_pk_fma_f32 v[60:61], v[60:61], v[138:139], v[190:191]
	v_pk_fma_f32 v[42:43], v[42:43], v[148:149], v[188:189]
	v_pk_fma_f32 v[40:41], v[40:41], v[146:147], v[186:187]
	v_pk_fma_f32 v[38:39], v[38:39], v[144:145], v[180:181]
	v_pk_fma_f32 v[36:37], v[36:37], v[142:143], v[178:179]
	v_mul_f32_e32 v190, v61, v61
	v_mul_f32_e32 v191, v63, v63
	v_mul_f32_e32 v186, v41, v41
	v_mul_f32_e32 v187, v43, v43
	v_mul_f32_e32 v178, v37, v37
	v_mul_f32_e32 v179, v39, v39
	v_fmac_f32_e32 v190, v60, v60
	v_fmac_f32_e32 v191, v62, v62
	v_fmac_f32_e32 v186, v40, v40
	v_fmac_f32_e32 v187, v42, v42
	v_fmac_f32_e32 v178, v36, v36
	v_fmac_f32_e32 v179, v38, v38
	s_waitcnt vmcnt(4)
	v_pk_fma_f32 v[34:35], v[34:35], v[136:137], v[184:185]
	v_pk_fma_f32 v[32:33], v[32:33], v[134:135], v[182:183]
	v_add_f32_e32 v190, v190, v191
	v_add_f32_e32 v186, v186, v187
	v_add_f32_e32 v178, v178, v179
	v_mul_f32_e32 v179, v33, v33
	v_mul_f32_e32 v180, v35, v35
	v_add_f32_e32 v186, v190, v186
	v_fmac_f32_e32 v179, v32, v32
	v_fmac_f32_e32 v180, v34, v34
	v_add_f32_e32 v178, v186, v178
	v_add_f32_e32 v179, v179, v180
	v_add_f32_e32 v178, v178, v179
	v_mov_b32_e32 v179, v178
	s_nop 1
	v_permlane16_swap_b32_e32 v179, v178
	s_waitcnt lgkmcnt(0)
	v_add_f32_e32 v178, v178, v179
	v_mov_b32_e32 v179, v178
	s_nop 1
	v_permlane32_swap_b32_e32 v179, v178
	s_and_saveexec_b64 s[50:51], s[38:39]
	s_cbranch_execz .LBB0_1542
	s_waitcnt lgkmcnt(0)
	v_add_f32_e32 v178, v178, v179
	ds_write_b32 v223, v178 offset:2304
.LBB0_1542:
	s_or_b64 exec, exec, s[50:51]
	s_waitcnt vmcnt(3)
	v_pk_fma_f32 v[30:31], v[30:31], v[140:141], v[176:177]
	v_pk_fma_f32 v[28:29], v[28:29], v[138:139], v[174:175]
	v_pk_fma_f32 v[26:27], v[26:27], v[148:149], v[168:169]
	v_pk_fma_f32 v[24:25], v[24:25], v[146:147], v[166:167]
	v_pk_fma_f32 v[22:23], v[22:23], v[144:145], v[164:165]
	v_pk_fma_f32 v[20:21], v[20:21], v[142:143], v[162:163]
	v_mul_f32_e32 v174, v29, v29
	v_mul_f32_e32 v175, v31, v31
	v_mul_f32_e32 v166, v25, v25
	v_mul_f32_e32 v167, v27, v27
	v_mul_f32_e32 v162, v21, v21
	v_mul_f32_e32 v163, v23, v23
	v_fmac_f32_e32 v174, v28, v28
	v_fmac_f32_e32 v175, v30, v30
	v_fmac_f32_e32 v166, v24, v24
	v_fmac_f32_e32 v167, v26, v26
	v_fmac_f32_e32 v162, v20, v20
	v_fmac_f32_e32 v163, v22, v22
	s_waitcnt vmcnt(2)
	v_pk_fma_f32 v[18:19], v[18:19], v[136:137], v[172:173]
	v_pk_fma_f32 v[16:17], v[16:17], v[134:135], v[170:171]
	v_add_f32_e32 v174, v174, v175
	v_add_f32_e32 v166, v166, v167
	v_add_f32_e32 v162, v162, v163
	v_mul_f32_e32 v163, v17, v17
	v_mul_f32_e32 v164, v19, v19
	v_add_f32_e32 v166, v174, v166
	v_fmac_f32_e32 v163, v16, v16
	v_fmac_f32_e32 v164, v18, v18
	v_add_f32_e32 v162, v166, v162
	v_add_f32_e32 v163, v163, v164
	v_add_f32_e32 v162, v162, v163
	v_mov_b32_e32 v163, v162
	s_nop 1
	v_permlane16_swap_b32_e32 v163, v162
	s_waitcnt lgkmcnt(0)
	v_add_f32_e32 v162, v162, v163
	v_mov_b32_e32 v163, v162
	s_nop 1
	v_permlane32_swap_b32_e32 v163, v162
	s_and_saveexec_b64 s[50:51], s[38:39]
	s_cbranch_execz .LBB0_1544
	s_waitcnt lgkmcnt(0)
	v_add_f32_e32 v162, v162, v163
	ds_write_b32 v223, v162 offset:2560
.LBB0_1544:
	s_or_b64 exec, exec, s[50:51]
	s_waitcnt vmcnt(1)
	v_pk_fma_f32 v[14:15], v[14:15], v[140:141], v[160:161]
	v_pk_fma_f32 v[12:13], v[12:13], v[138:139], v[158:159]
	v_mul_f32_e32 v139, v15, v15
	v_mul_f32_e32 v138, v13, v13
	v_fmac_f32_e32 v138, v12, v12
	v_fmac_f32_e32 v139, v14, v14
	v_pk_fma_f32 v[10:11], v[10:11], v[148:149], v[152:153]
	v_pk_fma_f32 v[8:9], v[8:9], v[146:147], v[150:151]
	v_pk_fma_f32 v[6:7], v[6:7], v[144:145], v[132:133]
	v_pk_fma_f32 v[4:5], v[4:5], v[142:143], v[130:131]
	v_add_f32_e32 v138, v138, v139
	v_mul_f32_e32 v139, v9, v9
	v_mul_f32_e32 v140, v11, v11
	v_mul_f32_e32 v130, v5, v5
	v_mul_f32_e32 v131, v7, v7
	v_fmac_f32_e32 v139, v8, v8
	v_fmac_f32_e32 v140, v10, v10
	v_fmac_f32_e32 v130, v4, v4
	v_fmac_f32_e32 v131, v6, v6
	s_waitcnt vmcnt(0)
	v_pk_fma_f32 v[2:3], v[2:3], v[136:137], v[156:157]
	v_pk_fma_f32 v[0:1], v[0:1], v[134:135], v[154:155]
	v_add_f32_e32 v139, v139, v140
	v_add_f32_e32 v130, v130, v131
	v_mul_f32_e32 v131, v1, v1
	v_mul_f32_e32 v132, v3, v3
	v_add_f32_e32 v138, v138, v139
	v_fmac_f32_e32 v131, v0, v0
	v_fmac_f32_e32 v132, v2, v2
	v_add_f32_e32 v130, v138, v130
	v_add_f32_e32 v131, v131, v132
	v_add_f32_e32 v130, v130, v131
	v_mov_b32_e32 v131, v130
	s_nop 1
	v_permlane16_swap_b32_e32 v131, v130
	s_waitcnt lgkmcnt(0)
	v_add_f32_e32 v130, v130, v131
	v_mov_b32_e32 v131, v130
	s_nop 1
	v_permlane32_swap_b32_e32 v131, v130
	s_and_saveexec_b64 s[50:51], s[38:39]
	s_cbranch_execz .LBB0_1546
	s_waitcnt lgkmcnt(0)
	v_add_f32_e32 v130, v130, v131
	ds_write_b32 v223, v130 offset:2816
